# v36 + mLSTM-out prologue (small table loads issued early, consumed after the 22 row loads) + grid barrier: non-leaders poll TOPGEN, ws pointer from spill lanes
# speedup vs baseline: 1.0029x; 1.0025x over previous
.LBB0_619:
	s_mov_b64 s[4:5], s[0:1]
	s_lshl_b32 s2, s86, 5
	v_mov_b32_e32 v106, v252
	s_and_b32 s6, s2, 0xffffc000
	s_load_dwordx2 s[2:3], s[4:5], 0xc0
	s_lshl_b32 s7, s86, 7
	s_and_b32 s10, s7, 0x3f80
	s_ashr_i32 s87, s86, 31
	s_bfe_u32 s11, s86, 0x20007
	s_or_b32 s8, s6, s10
	s_lshl_b64 s[6:7], s[86:87], 2
	s_waitcnt lgkmcnt(0)
	s_add_u32 s6, s2, s6
	s_addc_u32 s7, s3, s7
	v_mov_b32_e32 v0, 0xf482000
	global_load_dword v190, v0, s[6:7]
	v_readfirstlane_b32 s9, v106
	s_cmp_gt_u32 s9, 63
	v_and_b32_e32 v191, 63, v106
	s_cbranch_scc1 .LBB0_621
	v_lshl_or_b32 v2, v191, 1, s8
	v_ashrrev_i32_e32 v3, 31, v2
	v_lshlrev_b64 v[4:5], 5, v[2:3]
	v_or_b32_e32 v2, 1, v2
	s_add_u32 s6, s2, 0xf300000
	v_ashrrev_i32_e32 v3, 31, v2
	s_addc_u32 s7, s3, 0
	v_lshlrev_b64 v[2:3], 5, v[2:3]
	v_lshl_add_u64 v[4:5], s[6:7], 0, v[4:5]
	s_lshl_b32 s34, s11, 2
	v_lshl_add_u64 v[2:3], s[6:7], 0, v[2:3]
	v_lshl_add_u64 v[4:5], v[4:5], 0, s[34:35]
	v_lshl_add_u64 v[2:3], v[2:3], 0, s[34:35]
	global_load_dword v160, v[4:5], off
	global_load_dword v166, v[4:5], off offset:16
	global_load_dword v161, v[2:3], off
	s_nop 0
	global_load_dword v162, v[2:3], off offset:16
.LBB0_621:
	v_and_b32_e32 v0, 0xffffff80, v106
	v_cmp_eq_u32_e32 vcc, s65, v0
	s_and_saveexec_b64 s[6:7], vcc
	s_cbranch_execz .LBB0_623
	s_lshl_b64 s[12:13], s[86:87], 9
	s_add_u32 s12, s2, s12
	s_addc_u32 s13, s3, s13
	v_mov_b32_e32 v107, v1
	v_lshl_add_u64 v[2:3], v[106:107], 2, s[12:13]
	v_add_co_u32_e32 v2, vcc, 0xf3ff000, v2
	v_lshl_add_u32 v172, v106, 2, s57
	s_nop 0
	v_addc_co_u32_e32 v3, vcc, 0, v3, vcc
	global_load_dword v171, v[2:3], off offset:3584
	v_add_u32_e32 v172, 0xfffffe00, v172
.LBB0_623:
	s_or_b64 exec, exec, s[6:7]
	s_movk_i32 s6, 0x140
	v_cmp_gt_i32_e32 vcc, s6, v106
	s_and_saveexec_b64 s[6:7], vcc
	s_cbranch_execz .LBB0_625
	s_load_dwordx4 s[12:15], s[4:5], 0x40
	v_lshlrev_b32_e32 v2, 2, v106
	v_ashrrev_i32_e32 v0, 6, v106
	v_and_b32_e32 v8, 0xfc, v2
	v_lshlrev_b32_e32 v6, 10, v0
	s_waitcnt lgkmcnt(0)
	s_add_u32 s14, s14, s88
	s_addc_u32 s15, s15, s89
	s_add_u32 s12, s12, s22
	s_addc_u32 s13, s13, 0
	s_lshl_b32 s16, s11, 7
	v_or_b32_e32 v2, s16, v8
	s_addk_i32 s16, 0x180
	v_add_u32_e32 v3, s16, v8
	v_cmp_gt_u32_e32 vcc, s65, v8
	v_ashrrev_i32_e32 v7, 31, v6
	v_mov_b32_e32 v5, s15
	v_cndmask_b32_e32 v4, v3, v2, vcc
	v_lshl_add_u64 v[2:3], v[6:7], 2, s[12:13]
	v_cmp_gt_i32_e32 vcc, 4, v0
	v_mov_b32_e32 v0, s14
	s_nop 0
	v_cndmask_b32_e32 v3, v5, v3, vcc
	v_cndmask_b32_e32 v2, v0, v2, vcc
	v_lshlrev_b32_e32 v0, 2, v4
	v_lshl_add_u64 v[2:3], v[2:3], 0, v[0:1]
	global_load_dwordx4 v[176:179], v[2:3], off
	v_cndmask_b32_e32 v0, v228, v6, vcc
	v_lshlrev_b32_e32 v6, 2, v8
	v_add3_u32 v173, s33, v0, v6
.LBB0_625:
	s_or_b64 exec, exec, s[6:7]
	v_and_b32_e32 v0, 0xffffffe0, v106
	s_movk_i32 s6, 0x140
	v_cmp_ne_u32_e32 vcc, s6, v0
	s_and_saveexec_b64 s[6:7], vcc
	s_xor_b64 s[6:7], exec, s[6:7]
	s_lshl_b32 s34, s11, 7
	s_or_saveexec_b64 s[6:7], s[6:7]
	v_mov_b64_e32 v[108:109], s[34:35]
	v_mov_b32_e32 v18, s34
	s_xor_b64 exec, exec, s[6:7]
	s_cbranch_execz .LBB0_629
	s_load_dwordx2 s[4:5], s[4:5], 0x60
	v_mov_b32_e32 v0, 0xfffffb00
	v_lshl_add_u32 v0, v106, 2, v0
	s_waitcnt lgkmcnt(0)
	s_add_u32 s4, s4, s90
	s_addc_u32 s5, s5, s91
	s_lshl_b32 s34, s11, 7
	s_lshl_b32 s11, s11, 9
	s_add_u32 s4, s4, s11
	s_addc_u32 s5, s5, 0
	v_lshl_add_u64 v[2:3], v[0:1], 2, s[4:5]
	global_load_dwordx4 v[180:183], v[2:3], off
	v_lshl_add_u32 v0, v0, 2, 0
	v_add_u32_e32 v174, 0x21e00, v0
	v_mov_b64_e32 v[108:109], s[34:35]
	v_mov_b32_e32 v18, s34
.LBB0_629:
	s_or_b64 exec, exec, s[6:7]
	s_add_u32 s4, s2, 0xf500000
	s_addc_u32 s5, s3, 0
	s_lshl_b64 s[6:7], s[86:87], 15
	s_add_u32 s2, s2, s6
	v_lshlrev_b32_e32 v4, 3, v106
	v_lshlrev_b32_e32 v0, 4, v106
	s_addc_u32 s3, s3, s7
	v_and_b32_e32 v0, 0xf0, v0
	v_and_b32_e32 v16, 0xffffff80, v4
	v_lshl_add_u64 v[2:3], s[2:3], 0, v[0:1]
	v_add_u32_e32 v6, 0x1000, v16
	v_ashrrev_i32_e32 v107, 2, v106
	v_and_b32_e32 v192, 3, v106
	v_lshl_add_u64 v[14:15], v[2:3], 0, s[66:67]
	v_ashrrev_i32_e32 v17, 31, v16
	v_ashrrev_i32_e32 v7, 31, v6
	v_add_u32_e32 v76, s8, v107
	v_lshl_add_u64 v[2:3], v[16:17], 1, v[14:15]
	v_lshl_add_u64 v[6:7], v[6:7], 1, v[14:15]
	v_lshlrev_b32_e32 v111, 5, v192
	v_add_u32_e32 v77, s10, v107
	global_load_dwordx4 v[2:5], v[2:3], off
	v_or_b32_e32 v0, v18, v111
	global_load_dwordx4 v[10:13], v[6:7], off
	v_add_u32_e32 v6, 0x2000, v16
	v_add_u32_e32 v16, 0x3000, v16
	v_add_u32_e32 v20, -3, v76
	v_cmp_gt_i32_e32 vcc, 3, v77
	v_ashrrev_i32_e32 v7, 31, v6
	v_ashrrev_i32_e32 v17, 31, v16
	v_lshl_add_u64 v[74:75], v[0:1], 1, s[4:5]
	v_cndmask_b32_e32 v78, v20, v76, vcc
	v_add_u32_e32 v0, -2, v76
	v_cmp_gt_i32_e32 vcc, 2, v77
	v_lshl_add_u64 v[6:7], v[6:7], 1, v[14:15]
	v_lshl_add_u64 v[14:15], v[16:17], 1, v[14:15]
	v_mad_i64_i32 v[118:119], s[2:3], v78, s49, v[74:75]
	v_cndmask_b32_e32 v79, v0, v76, vcc
	v_cmp_lt_i32_e32 vcc, 0, v77
	global_load_dwordx4 v[6:9], v[6:7], off
	v_mad_i64_i32 v[120:121], s[2:3], v79, s49, v[74:75]
	global_load_dwordx4 v[14:17], v[14:15], off
	s_nop 0
	global_load_dwordx4 v[70:73], v[118:119], off offset:3088
	global_load_dwordx4 v[94:97], v[118:119], off offset:3072
	v_subbrev_co_u32_e64 v80, s[2:3], 0, v76, vcc
	global_load_dwordx4 v[62:65], v[120:121], off offset:3088
	global_load_dwordx4 v[86:89], v[120:121], off offset:3072
	v_mad_i64_i32 v[122:123], s[2:3], v80, s49, v[74:75]
	global_load_dwordx4 v[66:69], v[122:123], off offset:3088
	global_load_dwordx4 v[90:93], v[122:123], off offset:3072
	v_mad_i64_i32 v[124:125], s[2:3], v76, s49, v[74:75]
	global_load_dwordx4 v[58:61], v[124:125], off offset:3088
	global_load_dwordx4 v[82:85], v[124:125], off offset:3072
	s_mov_b64 s[2:3], 0x1000
	v_lshl_add_u64 v[20:21], v[74:75], 0, s[2:3]
	v_mov_b64_e32 v[18:19], s[4:5]
	v_mad_i64_i32 v[22:23], s[2:3], v78, s49, v[20:21]
	global_load_dwordx4 v[38:41], v[22:23], off offset:16
	global_load_dwordx4 v[54:57], v[22:23], off
	v_mad_i64_i32 v[22:23], s[2:3], v79, s49, v[20:21]
	v_mad_i64_i32 v[18:19], s[2:3], v76, s49, v[18:19]
	global_load_dwordx4 v[34:37], v[22:23], off offset:16
	global_load_dwordx4 v[50:53], v[22:23], off
	v_mad_i64_i32 v[22:23], s[2:3], v80, s49, v[20:21]
	v_mad_i64_i32 v[20:21], s[2:3], v76, s49, v[20:21]
	v_lshl_add_u64 v[18:19], v[108:109], 1, v[18:19]
	v_lshlrev_b32_e32 v0, 6, v192
	v_lshl_add_u64 v[18:19], v[18:19], 0, v[0:1]
	s_mov_b64 s[2:3], 0x1400
	v_lshl_add_u64 v[116:117], v[18:19], 0, s[2:3]
	s_movk_i32 s2, 0x1000
	v_add_co_u32_e64 v18, s[2:3], s2, v18
	v_lshlrev_b32_e32 v195, 7, v192
	s_nop 0
	v_addc_co_u32_e64 v19, s[2:3], 0, v19, s[2:3]
	v_cmp_lt_i32_e64 s[2:3], 2, v77
	v_cndmask_b32_e64 v110, 0, 1.0, vcc
	v_cmp_lt_i32_e32 vcc, -1, v77
	v_cndmask_b32_e64 v114, 0, 1.0, s[2:3]
	v_cmp_lt_i32_e64 s[2:3], 1, v77
	v_lshlrev_b32_e32 v77, 1, v107
	v_add_u32_e32 v113, s33, v195
	v_cndmask_b32_e64 v112, 0, 1.0, s[2:3]
	s_mov_b64 s[2:3], 0x1020
	v_lshl_add_u64 v[74:75], v[74:75], 0, s[2:3]
	v_mad_i64_i32 v[126:127], s[2:3], v78, s49, v[74:75]
	v_mad_i64_i32 v[128:129], s[2:3], v79, s49, v[74:75]
	v_mad_i64_i32 v[130:131], s[2:3], v80, s49, v[74:75]
	v_mad_i64_i32 v[132:133], s[2:3], v76, s49, v[74:75]
	v_add_u32_e32 v74, s19, v195
	global_load_dwordx4 v[30:33], v[22:23], off offset:16
	global_load_dwordx4 v[46:49], v[22:23], off
	global_load_dwordx4 v[26:29], v[20:21], off offset:16
	global_load_dwordx4 v[42:45], v[20:21], off
	s_nop 0
	global_load_dwordx4 v[22:25], v[18:19], off offset:1024
	s_nop 0
	global_load_dwordx4 v[18:21], v[116:117], off offset:16
	s_waitcnt vmcnt(22)
	s_mov_b64 s[42:43], vcc
	s_cmp_gt_u32 s9, 63
	s_cbranch_scc1 .Ldpro_1
	v_mov_b32_e32 v163, v1
	v_lshl_add_u32 v167, v191, 2, -4
	v_lshl_add_u32 v168, v191, 3, 0
	v_add_u32_e32 v169, 0x20000, v168
	v_cmp_ne_u32_e32 vcc, 0, v191
	v_add_u32_e32 v170, 0x20400, v168
	v_add_f32_e32 v166, v166, v162
	s_nop 1
	v_add_f32_dpp v166, v166, v166 row_shr:1 row_mask:0xf bank_mask:0xf bound_ctrl:1
	s_nop 1
	v_add_f32_dpp v166, v166, v166 row_shr:2 row_mask:0xf bank_mask:0xf bound_ctrl:1
	s_nop 1
	v_add_f32_dpp v166, v166, v166 row_shr:4 row_mask:0xf bank_mask:0xf bound_ctrl:1
	s_nop 1
	v_add_f32_dpp v166, v166, v166 row_shr:8 row_mask:0xf bank_mask:0xf bound_ctrl:1
	s_nop 1
	v_mov_b32_dpp v163, v166 row_bcast:15 row_mask:0xa bank_mask:0xf
	v_add_f32_e32 v166, v166, v163
	v_mov_b32_e32 v163, v1
	s_nop 1
	v_mov_b32_dpp v163, v166 row_bcast:31 row_mask:0xc bank_mask:0xf
	v_add_f32_e32 v163, v166, v163
	v_sub_f32_e32 v162, v163, v162
	v_pk_add_f32 v[164:165], v[160:161], v[162:163] neg_lo:[0,1] neg_hi:[0,1]
	v_mov_b32_e32 v160, 0xff800000
	v_max_f32_e32 v166, v164, v165
	v_mov_b32_e32 v161, 0xff800000
	ds_write_b64 v169, v[164:165]
	ds_write_b64 v170, v[162:163]
	v_mov_b32_dpp v160, v166 row_shr:1 row_mask:0xf bank_mask:0xf
	v_max_f32_e32 v160, v160, v160
	v_max_f32_e32 v166, v166, v160
	v_mov_b32_e32 v160, 0xff800000
	v_max_f32_e32 v163, v190, v190
	s_nop 0
	v_mov_b32_dpp v160, v166 row_shr:2 row_mask:0xf bank_mask:0xf
	v_max_f32_e32 v160, v160, v160
	v_max_f32_e32 v166, v166, v160
	v_mov_b32_e32 v160, 0xff800000
	s_nop 1
	v_mov_b32_dpp v160, v166 row_shr:4 row_mask:0xf bank_mask:0xf
	v_max_f32_e32 v160, v160, v160
	v_max_f32_e32 v166, v166, v160
	v_mov_b32_e32 v160, 0xff800000
	s_nop 1
	v_mov_b32_dpp v160, v166 row_shr:8 row_mask:0xf bank_mask:0xf
	v_max_f32_e32 v160, v160, v160
	v_max_f32_e32 v166, v166, v160
	v_mov_b32_e32 v160, 0xff800000
	s_nop 1
	v_mov_b32_dpp v160, v166 row_bcast:15 row_mask:0xa bank_mask:0xf
	v_max_f32_e32 v160, v160, v160
	v_max_f32_e32 v166, v166, v160
	v_mov_b32_e32 v160, 0xff800000
	s_nop 1
	v_mov_b32_dpp v160, v166 row_bcast:31 row_mask:0xc bank_mask:0xf
	v_max_f32_e32 v160, v160, v160
	v_max_f32_e32 v166, v166, v160
	ds_bpermute_b32 v160, v167, v166
	v_max_f32_e32 v163, v166, v163
	s_waitcnt lgkmcnt(0)
	v_cndmask_b32_e32 v160, v161, v160, vcc
	v_max3_f32 v162, v160, v164, v190
	v_add_u32_e32 v164, 0x20200, v168
	ds_write_b64 v164, v[162:163]
.Ldpro_1:
	s_mov_b64 s[28:29], exec
	v_and_b32_e32 v175, 0xffffff80, v106
	v_cmp_eq_u32_e32 vcc, s65, v175
	s_and_b64 exec, exec, vcc
	ds_write_b32 v172, v171
	s_mov_b64 exec, s[28:29]
	s_movk_i32 s36, 0x140
	v_cmp_gt_i32_e32 vcc, s36, v106
	s_and_b64 exec, exec, vcc
	ds_write_b128 v173, v[176:179]
	s_mov_b64 exec, s[28:29]
	v_and_b32_e32 v175, 0xffffffe0, v106
	v_cmp_eq_u32_e32 vcc, s36, v175
	s_and_b64 exec, exec, vcc
	ds_write_b128 v174, v[180:183]
	s_mov_b64 exec, s[28:29]
	s_mov_b64 vcc, s[42:43]
	s_waitcnt lgkmcnt(0)
	s_barrier
	v_and_b32_e32 v196, 14, v77
	ds_read_b128 v[102:105], v74
	ds_read_b128 v[98:101], v74 offset:16
	ds_read_b128 v[78:81], v74 offset:32
	ds_read_b128 v[74:77], v74 offset:48
	ds_read_b128 v[134:137], v113
	ds_read_b128 v[138:141], v113 offset:16
	ds_read_b128 v[142:145], v113 offset:32
	ds_read_b128 v[154:157], v113 offset:48
	ds_read_b128 v[198:201], v113 offset:2096
	s_waitcnt lgkmcnt(4)
	v_pk_mul_f32 v[178:179], v[114:115], v[134:135] op_sel_hi:[0,1]
	s_waitcnt lgkmcnt(3)
	v_pk_mul_f32 v[152:153], v[114:115], v[140:141] op_sel_hi:[0,1]
	s_waitcnt lgkmcnt(2)
	v_pk_mul_f32 v[140:141], v[114:115], v[144:145] op_sel_hi:[0,1]
	v_pk_mul_f32 v[148:149], v[114:115], v[142:143] op_sel_hi:[0,1]
	ds_read_b128 v[142:145], v113 offset:1024
	s_waitcnt lgkmcnt(2)
	v_pk_mul_f32 v[134:135], v[114:115], v[156:157] op_sel_hi:[0,1]
	ds_read_b128 v[156:159], v113 offset:2048
	v_pk_mul_f32 v[172:173], v[114:115], v[136:137] op_sel_hi:[0,1]
	v_pk_mul_f32 v[136:137], v[114:115], v[154:155] op_sel_hi:[0,1]
	s_waitcnt lgkmcnt(1)
	v_pk_mul_f32 v[176:177], v[112:113], v[144:145] op_sel_hi:[0,1]
	v_pk_mul_f32 v[184:185], v[112:113], v[142:143] op_sel_hi:[0,1]
	ds_read_b128 v[142:145], v113 offset:1040
	s_waitcnt lgkmcnt(1)
	v_pk_mul_f32 v[186:187], v[110:111], v[158:159] op_sel_hi:[0,1]
	v_pk_mul_f32 v[202:203], v[110:111], v[156:157] op_sel_hi:[0,1]
	ds_read_b128 v[156:159], v113 offset:2064
	v_pk_mul_f32 v[162:163], v[114:115], v[138:139] op_sel_hi:[0,1]
	s_waitcnt lgkmcnt(1)
	v_pk_mul_f32 v[160:161], v[112:113], v[144:145] op_sel_hi:[0,1]
	v_pk_mul_f32 v[168:169], v[112:113], v[142:143] op_sel_hi:[0,1]
	ds_read_b128 v[142:145], v113 offset:1056
	s_waitcnt lgkmcnt(1)
	v_pk_mul_f32 v[174:175], v[110:111], v[158:159] op_sel_hi:[0,1]
	v_pk_mul_f32 v[182:183], v[110:111], v[156:157] op_sel_hi:[0,1]
	ds_read_b128 v[156:159], v113 offset:2080
	v_pk_mul_f32 v[150:151], v[110:111], v[198:199] op_sel_hi:[0,1]
	s_waitcnt lgkmcnt(1)
	v_pk_mul_f32 v[146:147], v[112:113], v[144:145] op_sel_hi:[0,1]
	v_pk_mul_f32 v[154:155], v[112:113], v[142:143] op_sel_hi:[0,1]
	ds_read_b128 v[142:145], v113 offset:1072
	v_cndmask_b32_e64 v0, 0, 1.0, vcc
	s_waitcnt lgkmcnt(1)
	v_pk_mul_f32 v[166:167], v[110:111], v[156:157] op_sel_hi:[0,1]
	v_pk_mul_f32 v[158:159], v[110:111], v[158:159] op_sel_hi:[0,1]
	v_lshlrev_b32_e32 v194, 8, v107
	s_waitcnt lgkmcnt(0)
	v_pk_mul_f32 v[138:139], v[112:113], v[144:145] op_sel_hi:[0,1]
	v_pk_mul_f32 v[144:145], v[110:111], v[200:201] op_sel_hi:[0,1]
	ds_read_b128 v[198:201], v113 offset:3072
	v_pk_mul_f32 v[142:143], v[112:113], v[142:143] op_sel_hi:[0,1]
	v_and_b32_e32 v193, 15, v107
	s_add_i32 s23, 0, 0x10000
	s_movk_i32 s2, 0x50
	s_waitcnt lgkmcnt(0)
	v_pk_mul_f32 v[204:205], v[0:1], v[200:201] op_sel_hi:[0,1]
	v_pk_mul_f32 v[206:207], v[0:1], v[198:199] op_sel_hi:[0,1]
	ds_read_b128 v[198:201], v113 offset:3088
	s_add_i32 s36, 0, 0x18000
	v_cmp_eq_u32_e32 vcc, 0, v192
	s_waitcnt lgkmcnt(0)
	v_pk_mul_f32 v[208:209], v[0:1], v[200:201] op_sel_hi:[0,1]
	v_pk_mul_f32 v[210:211], v[0:1], v[198:199] op_sel_hi:[0,1]
	ds_read_b128 v[198:201], v113 offset:3104
	s_waitcnt lgkmcnt(0)
	v_pk_mul_f32 v[170:171], v[0:1], v[200:201] op_sel_hi:[0,1]
	v_pk_mul_f32 v[180:181], v[0:1], v[198:199] op_sel_hi:[0,1]
	ds_read_b128 v[198:201], v113 offset:3120
	s_waitcnt lgkmcnt(0)
	v_pk_mul_f32 v[164:165], v[0:1], v[198:199] op_sel_hi:[0,1]
	s_waitcnt vmcnt(16)
	v_lshlrev_b32_e32 v198, 16, v94
	v_and_b32_e32 v199, 0xffff0000, v94
	v_pk_fma_f32 v[102:103], v[178:179], v[198:199], v[102:103]
	s_waitcnt vmcnt(14)
	v_lshlrev_b32_e32 v178, 16, v86
	v_and_b32_e32 v179, 0xffff0000, v86
	v_pk_fma_f32 v[102:103], v[184:185], v[178:179], v[102:103]
	s_waitcnt vmcnt(12)
	v_lshlrev_b32_e32 v178, 16, v90
	v_and_b32_e32 v179, 0xffff0000, v90
	v_pk_fma_f32 v[102:103], v[202:203], v[178:179], v[102:103]
	s_waitcnt vmcnt(10)
	v_lshlrev_b32_e32 v178, 16, v82
	v_and_b32_e32 v179, 0xffff0000, v82
	v_pk_fma_f32 v[102:103], v[206:207], v[178:179], v[102:103]
	v_lshlrev_b32_e32 v94, 16, v95
	v_mul_f32_e32 v82, 0xbfb8aa3b, v102
	v_exp_f32_e32 v82, v82
	v_and_b32_e32 v95, 0xffff0000, v95
	v_pk_fma_f32 v[94:95], v[172:173], v[94:95], v[104:105]
	v_lshlrev_b32_e32 v86, 16, v87
	v_add_f32_e32 v82, 1.0, v82
	v_rcp_f32_e32 v178, v82
	v_mul_f32_e32 v82, 0xbfb8aa3b, v103
	v_exp_f32_e32 v82, v82
	v_and_b32_e32 v87, 0xffff0000, v87
	v_pk_fma_f32 v[86:87], v[176:177], v[86:87], v[94:95]
	v_lshlrev_b32_e32 v90, 16, v91
	v_add_f32_e32 v82, 1.0, v82
	v_and_b32_e32 v91, 0xffff0000, v91
	v_rcp_f32_e32 v179, v82
	v_pk_fma_f32 v[86:87], v[186:187], v[90:91], v[86:87]
	v_lshlrev_b32_e32 v82, 16, v83
	v_and_b32_e32 v83, 0xffff0000, v83
	v_pk_fma_f32 v[82:83], v[204:205], v[82:83], v[86:87]
	v_lshlrev_b32_e32 v90, 16, v88
	v_mul_f32_e32 v86, 0xbfb8aa3b, v82
	v_mul_f32_e32 v87, 0xbfb8aa3b, v83
	v_exp_f32_e32 v86, v86
	v_exp_f32_e32 v87, v87
	v_and_b32_e32 v91, 0xffff0000, v88
	v_lshlrev_b32_e32 v88, 16, v89
	v_add_f32_e32 v86, 1.0, v86
	v_add_f32_e32 v87, 1.0, v87
	v_rcp_f32_e32 v86, v86
	v_rcp_f32_e32 v87, v87
	v_and_b32_e32 v89, 0xffff0000, v89
	v_pk_mul_f32 v[156:157], v[0:1], v[200:201] op_sel_hi:[0,1]
	v_pk_mul_f32 v[102:103], v[102:103], v[178:179]
	v_pk_mul_f32 v[82:83], v[82:83], v[86:87]
	v_lshlrev_b32_e32 v86, 16, v96
	v_and_b32_e32 v87, 0xffff0000, v96
	v_pk_fma_f32 v[86:87], v[162:163], v[86:87], v[98:99]
	v_lshlrev_b32_e32 v162, 2, v192
	v_pk_fma_f32 v[86:87], v[168:169], v[90:91], v[86:87]
	v_lshlrev_b32_e32 v90, 16, v92
	v_and_b32_e32 v91, 0xffff0000, v92
	v_pk_fma_f32 v[86:87], v[182:183], v[90:91], v[86:87]
	v_lshlrev_b32_e32 v90, 16, v84
	v_and_b32_e32 v91, 0xffff0000, v84
	v_pk_fma_f32 v[86:87], v[210:211], v[90:91], v[86:87]
	v_or_b32_e32 v182, 16, v111
	v_mul_f32_e32 v84, 0xbfb8aa3b, v86
	v_exp_f32_e32 v84, v84
	v_or_b32_e32 v163, 1, v162
	v_add_f32_e32 v84, 1.0, v84
	v_rcp_f32_e32 v90, v84
	v_mul_f32_e32 v84, 0xbfb8aa3b, v87
	v_exp_f32_e32 v84, v84
	s_nop 0
	v_add_f32_e32 v84, 1.0, v84
	v_rcp_f32_e32 v91, v84
	v_lshlrev_b32_e32 v84, 16, v85
	v_and_b32_e32 v85, 0xffff0000, v85
	v_pk_mul_f32 v[86:87], v[86:87], v[90:91]
	v_lshlrev_b32_e32 v90, 16, v97
	v_and_b32_e32 v91, 0xffff0000, v97
	v_pk_fma_f32 v[90:91], v[152:153], v[90:91], v[100:101]
	s_nop 0
	v_pk_fma_f32 v[88:89], v[160:161], v[88:89], v[90:91]
	v_lshlrev_b32_e32 v90, 16, v93
	v_and_b32_e32 v91, 0xffff0000, v93
	v_pk_fma_f32 v[88:89], v[174:175], v[90:91], v[88:89]
	s_nop 0
	v_pk_fma_f32 v[84:85], v[208:209], v[84:85], v[88:89]
	s_nop 0
	v_mul_f32_e32 v88, 0xbfb8aa3b, v84
	v_mul_f32_e32 v89, 0xbfb8aa3b, v85
	v_exp_f32_e32 v88, v88
	v_exp_f32_e32 v89, v89
	v_add_f32_e32 v88, 1.0, v88
	v_add_f32_e32 v89, 1.0, v89
	v_rcp_f32_e32 v88, v88
	v_rcp_f32_e32 v89, v89
	s_nop 0
	v_pk_mul_f32 v[84:85], v[84:85], v[88:89]
	v_lshlrev_b32_e32 v88, 16, v70
	v_and_b32_e32 v89, 0xffff0000, v70
	v_pk_fma_f32 v[78:79], v[148:149], v[88:89], v[78:79]
	v_lshlrev_b32_e32 v88, 16, v62
	v_and_b32_e32 v89, 0xffff0000, v62
	v_pk_fma_f32 v[78:79], v[154:155], v[88:89], v[78:79]
	v_lshlrev_b32_e32 v88, 16, v66
	v_and_b32_e32 v89, 0xffff0000, v66
	v_pk_fma_f32 v[78:79], v[166:167], v[88:89], v[78:79]
	v_lshlrev_b32_e32 v88, 16, v58
	v_and_b32_e32 v89, 0xffff0000, v58
	v_pk_fma_f32 v[78:79], v[180:181], v[88:89], v[78:79]
	v_lshlrev_b32_e32 v70, 16, v71
	v_mul_f32_e32 v58, 0xbfb8aa3b, v78
	v_exp_f32_e32 v58, v58
	v_and_b32_e32 v71, 0xffff0000, v71
	v_pk_fma_f32 v[70:71], v[140:141], v[70:71], v[80:81]
	v_lshlrev_b32_e32 v62, 16, v63
	v_add_f32_e32 v58, 1.0, v58
	v_rcp_f32_e32 v88, v58
	v_mul_f32_e32 v58, 0xbfb8aa3b, v79
	v_exp_f32_e32 v58, v58
	v_and_b32_e32 v63, 0xffff0000, v63
	v_pk_fma_f32 v[62:63], v[146:147], v[62:63], v[70:71]
	v_lshlrev_b32_e32 v66, 16, v67
	v_add_f32_e32 v58, 1.0, v58
	v_and_b32_e32 v67, 0xffff0000, v67
	v_rcp_f32_e32 v89, v58
	v_pk_fma_f32 v[62:63], v[158:159], v[66:67], v[62:63]
	v_lshlrev_b32_e32 v58, 16, v59
	v_and_b32_e32 v59, 0xffff0000, v59
	v_pk_fma_f32 v[58:59], v[170:171], v[58:59], v[62:63]
	v_pk_mul_f32 v[78:79], v[78:79], v[88:89]
	v_mul_f32_e32 v62, 0xbfb8aa3b, v58
	v_mul_f32_e32 v63, 0xbfb8aa3b, v59
	v_exp_f32_e32 v62, v62
	v_exp_f32_e32 v63, v63
	v_add_f32_e32 v62, 1.0, v62
	v_add_f32_e32 v63, 1.0, v63
	v_rcp_f32_e32 v62, v62
	v_rcp_f32_e32 v63, v63
	s_nop 0
	v_pk_mul_f32 v[66:67], v[58:59], v[62:63]
	v_lshlrev_b32_e32 v58, 16, v72
	v_and_b32_e32 v59, 0xffff0000, v72
	v_pk_fma_f32 v[58:59], v[136:137], v[58:59], v[74:75]
	v_lshlrev_b32_e32 v62, 16, v64
	v_and_b32_e32 v63, 0xffff0000, v64
	v_pk_fma_f32 v[58:59], v[142:143], v[62:63], v[58:59]
	v_lshlrev_b32_e32 v62, 16, v68
	v_and_b32_e32 v63, 0xffff0000, v68
	v_pk_fma_f32 v[58:59], v[150:151], v[62:63], v[58:59]
	v_lshlrev_b32_e32 v62, 16, v60
	v_and_b32_e32 v63, 0xffff0000, v60
	v_pk_fma_f32 v[58:59], v[164:165], v[62:63], v[58:59]
	v_or_b32_e32 v74, 0x200, v195
	v_mul_f32_e32 v60, 0xbfb8aa3b, v58
	v_exp_f32_e32 v60, v60
	s_nop 0
	v_add_f32_e32 v60, 1.0, v60
	v_rcp_f32_e32 v62, v60
	v_mul_f32_e32 v60, 0xbfb8aa3b, v59
	v_exp_f32_e32 v60, v60
	s_nop 0
	v_add_f32_e32 v60, 1.0, v60
	v_rcp_f32_e32 v63, v60
	v_lshlrev_b32_e32 v60, 16, v61
	v_and_b32_e32 v61, 0xffff0000, v61
	v_pk_mul_f32 v[70:71], v[58:59], v[62:63]
	v_lshlrev_b32_e32 v58, 16, v73
	v_and_b32_e32 v59, 0xffff0000, v73
	v_pk_fma_f32 v[58:59], v[134:135], v[58:59], v[76:77]
	v_lshlrev_b32_e32 v62, 16, v65
	v_and_b32_e32 v63, 0xffff0000, v65
	v_pk_fma_f32 v[58:59], v[138:139], v[62:63], v[58:59]
	v_lshlrev_b32_e32 v62, 16, v69
	v_and_b32_e32 v63, 0xffff0000, v69
	v_pk_fma_f32 v[58:59], v[144:145], v[62:63], v[58:59]
	v_cvt_pk_bf16_f32 v63, v66, v67
	v_pk_fma_f32 v[58:59], v[156:157], v[60:61], v[58:59]
	v_bitop3_b32 v66, v162, v107, 15 bitop3:0x78
	v_mul_f32_e32 v60, 0xbfb8aa3b, v58
	v_mul_f32_e32 v61, 0xbfb8aa3b, v59
	v_exp_f32_e32 v60, v60
	v_exp_f32_e32 v61, v61
	v_lshlrev_b32_e32 v165, 4, v66
	v_or_b32_e32 v66, v165, v194
	v_add_f32_e32 v60, 1.0, v60
	v_add_f32_e32 v61, 1.0, v61
	v_rcp_f32_e32 v60, v60
	v_rcp_f32_e32 v61, v61
	v_add_u32_e32 v113, 0, v66
	v_cvt_pk_bf16_f32 v62, v78, v79
	v_cvt_pk_bf16_f32 v64, v70, v71
	v_pk_mul_f32 v[68:69], v[58:59], v[60:61]
	v_cvt_pk_bf16_f32 v58, v102, v103
	v_cvt_pk_bf16_f32 v59, v82, v83
	v_cvt_pk_bf16_f32 v60, v86, v87
	v_cvt_pk_bf16_f32 v61, v84, v85
	ds_write_b128 v113, v[58:61]
	v_bitop3_b32 v58, v162, v193, 1 bitop3:0x36
	v_lshlrev_b32_e32 v164, 4, v58
	v_or_b32_e32 v58, v164, v194
	v_cvt_pk_bf16_f32 v65, v68, v69
	v_add_u32_e32 v115, 0, v58
	ds_write_b128 v115, v[62:65]
	v_add_u32_e32 v58, s19, v74
	v_add_u32_e32 v102, s33, v74
	ds_read_b128 v[70:73], v58
	ds_read_b128 v[66:69], v58 offset:16
	ds_read_b128 v[62:65], v58 offset:32
	ds_read_b128 v[58:61], v58 offset:48
	ds_read_b128 v[74:77], v102
	ds_read_b128 v[78:81], v102 offset:16
	ds_read_b128 v[82:85], v102 offset:32
	ds_read_b128 v[90:93], v102 offset:48
	ds_read_b128 v[156:159], v102 offset:3072
	s_waitcnt lgkmcnt(4)
	v_pk_mul_f32 v[142:143], v[114:115], v[76:77] op_sel_hi:[0,1]
	v_pk_mul_f32 v[152:153], v[114:115], v[74:75] op_sel_hi:[0,1]
	s_waitcnt lgkmcnt(3)
	v_pk_mul_f32 v[98:99], v[114:115], v[80:81] op_sel_hi:[0,1]
	s_waitcnt lgkmcnt(2)
	v_pk_mul_f32 v[80:81], v[114:115], v[84:85] op_sel_hi:[0,1]
	v_pk_mul_f32 v[88:89], v[114:115], v[82:83] op_sel_hi:[0,1]
	s_waitcnt lgkmcnt(1)
	v_pk_mul_f32 v[74:75], v[114:115], v[92:93] op_sel_hi:[0,1]
	v_pk_mul_f32 v[76:77], v[114:115], v[90:91] op_sel_hi:[0,1]
	ds_read_b128 v[82:85], v102 offset:1024
	ds_read_b128 v[90:93], v102 offset:2048
	s_waitcnt lgkmcnt(2)
	v_pk_mul_f32 v[168:169], v[0:1], v[158:159] op_sel_hi:[0,1]
	v_pk_mul_f32 v[170:171], v[0:1], v[156:157] op_sel_hi:[0,1]
	ds_read_b128 v[156:159], v102 offset:3088
	s_waitcnt lgkmcnt(2)
	v_pk_mul_f32 v[146:147], v[112:113], v[84:85] op_sel_hi:[0,1]
	v_pk_mul_f32 v[154:155], v[112:113], v[82:83] op_sel_hi:[0,1]
	ds_read_b128 v[82:85], v102 offset:1040
	s_waitcnt lgkmcnt(2)
	v_pk_mul_f32 v[160:161], v[110:111], v[92:93] op_sel_hi:[0,1]
	v_pk_mul_f32 v[166:167], v[110:111], v[90:91] op_sel_hi:[0,1]
	ds_read_b128 v[90:93], v102 offset:2064
	s_waitcnt lgkmcnt(2)
	v_pk_mul_f32 v[150:151], v[0:1], v[158:159] op_sel_hi:[0,1]
	v_pk_mul_f32 v[172:173], v[0:1], v[156:157] op_sel_hi:[0,1]
	ds_read_b128 v[156:159], v102 offset:3104
	s_waitcnt lgkmcnt(2)
	v_pk_mul_f32 v[100:101], v[112:113], v[84:85] op_sel_hi:[0,1]
	v_pk_mul_f32 v[138:139], v[112:113], v[82:83] op_sel_hi:[0,1]
	ds_read_b128 v[82:85], v102 offset:1056
	s_waitcnt lgkmcnt(2)
	v_pk_mul_f32 v[140:141], v[110:111], v[92:93] op_sel_hi:[0,1]
	v_pk_mul_f32 v[148:149], v[110:111], v[90:91] op_sel_hi:[0,1]
	ds_read_b128 v[90:93], v102 offset:2080
	s_waitcnt lgkmcnt(2)
	v_pk_mul_f32 v[136:137], v[0:1], v[158:159] op_sel_hi:[0,1]
	v_pk_mul_f32 v[144:145], v[0:1], v[156:157] op_sel_hi:[0,1]
	ds_read_b128 v[156:159], v102 offset:3120
	s_waitcnt lgkmcnt(2)
	v_pk_mul_f32 v[86:87], v[112:113], v[84:85] op_sel_hi:[0,1]
	v_pk_mul_f32 v[94:95], v[112:113], v[82:83] op_sel_hi:[0,1]
	ds_read_b128 v[82:85], v102 offset:1072
	s_waitcnt lgkmcnt(2)
	v_pk_mul_f32 v[96:97], v[110:111], v[92:93] op_sel_hi:[0,1]
	v_pk_mul_f32 v[104:105], v[110:111], v[90:91] op_sel_hi:[0,1]
	ds_read_b128 v[90:93], v102 offset:2096
	s_waitcnt lgkmcnt(2)
	v_pk_mul_f32 v[102:103], v[0:1], v[156:157] op_sel_hi:[0,1]
	s_waitcnt vmcnt(8)
	v_lshlrev_b32_e32 v156, 16, v54
	v_and_b32_e32 v157, 0xffff0000, v54
	v_lshlrev_b32_e32 v54, 16, v55
	v_and_b32_e32 v55, 0xffff0000, v55
	v_pk_fma_f32 v[70:71], v[152:153], v[156:157], v[70:71]
	s_waitcnt vmcnt(6)
	v_lshlrev_b32_e32 v152, 16, v50
	v_and_b32_e32 v153, 0xffff0000, v50
	v_pk_fma_f32 v[54:55], v[142:143], v[54:55], v[72:73]
	v_lshlrev_b32_e32 v50, 16, v51
	v_and_b32_e32 v51, 0xffff0000, v51
	v_pk_fma_f32 v[70:71], v[154:155], v[152:153], v[70:71]
	s_waitcnt vmcnt(4)
	v_lshlrev_b32_e32 v152, 16, v46
	v_and_b32_e32 v153, 0xffff0000, v46
	v_pk_fma_f32 v[50:51], v[146:147], v[50:51], v[54:55]
	v_lshlrev_b32_e32 v46, 16, v47
	v_and_b32_e32 v47, 0xffff0000, v47
	v_pk_fma_f32 v[46:47], v[160:161], v[46:47], v[50:51]
	s_waitcnt vmcnt(2)
	v_lshlrev_b32_e32 v50, 16, v43
	v_and_b32_e32 v51, 0xffff0000, v43
	v_pk_fma_f32 v[46:47], v[168:169], v[50:51], v[46:47]
	v_pk_mul_f32 v[134:135], v[114:115], v[78:79] op_sel_hi:[0,1]
	v_mul_f32_e32 v43, 0xbfb8aa3b, v46
	v_exp_f32_e32 v43, v43
	s_waitcnt lgkmcnt(1)
	v_pk_mul_f32 v[82:83], v[112:113], v[82:83] op_sel_hi:[0,1]
	s_waitcnt lgkmcnt(0)
	v_pk_mul_f32 v[90:91], v[110:111], v[90:91] op_sel_hi:[0,1]
	v_pk_mul_f32 v[78:79], v[112:113], v[84:85] op_sel_hi:[0,1]
	v_add_f32_e32 v43, 1.0, v43
	v_rcp_f32_e32 v50, v43
	v_mul_f32_e32 v43, 0xbfb8aa3b, v47
	v_exp_f32_e32 v43, v43
	v_pk_mul_f32 v[84:85], v[110:111], v[92:93] op_sel_hi:[0,1]
	v_pk_fma_f32 v[70:71], v[166:167], v[152:153], v[70:71]
	v_lshlrev_b32_e32 v152, 16, v42
	v_add_f32_e32 v43, 1.0, v43
	v_rcp_f32_e32 v51, v43
	v_and_b32_e32 v153, 0xffff0000, v42
	v_pk_mul_f32 v[92:93], v[0:1], v[158:159] op_sel_hi:[0,1]
	v_pk_fma_f32 v[70:71], v[170:171], v[152:153], v[70:71]
	v_pk_mul_f32 v[46:47], v[46:47], v[50:51]
	v_lshlrev_b32_e32 v50, 16, v52
	v_pk_mul_f32 v[46:47], v[46:47], s[64:65] op_sel_hi:[1,0]
	v_and_b32_e32 v51, 0xffff0000, v52
	v_cvt_pk_bf16_f32 v43, v46, v47
	v_lshlrev_b32_e32 v46, 16, v56
	v_and_b32_e32 v47, 0xffff0000, v56
	v_pk_fma_f32 v[46:47], v[134:135], v[46:47], v[66:67]
	v_mul_f32_e32 v42, 0xbfb8aa3b, v70
	v_pk_fma_f32 v[46:47], v[138:139], v[50:51], v[46:47]
	v_lshlrev_b32_e32 v50, 16, v48
	v_and_b32_e32 v51, 0xffff0000, v48
	v_pk_fma_f32 v[46:47], v[148:149], v[50:51], v[46:47]
	v_lshlrev_b32_e32 v50, 16, v44
	v_and_b32_e32 v51, 0xffff0000, v44
	v_pk_fma_f32 v[46:47], v[172:173], v[50:51], v[46:47]
	v_lshlrev_b32_e32 v48, 16, v49
	v_mul_f32_e32 v44, 0xbfb8aa3b, v46
	v_exp_f32_e32 v44, v44
	v_and_b32_e32 v49, 0xffff0000, v49
	v_exp_f32_e32 v42, v42
	v_add_f32_e32 v44, 1.0, v44
	v_rcp_f32_e32 v50, v44
	v_mul_f32_e32 v44, 0xbfb8aa3b, v47
	v_exp_f32_e32 v44, v44
	v_add_f32_e32 v42, 1.0, v42
	v_rcp_f32_e32 v152, v42
	v_mul_f32_e32 v42, 0xbfb8aa3b, v71
	v_add_f32_e32 v44, 1.0, v44
	v_rcp_f32_e32 v51, v44
	v_exp_f32_e32 v42, v42
	v_pk_mul_f32 v[46:47], v[46:47], v[50:51]
	s_nop 0
	v_pk_mul_f32 v[46:47], v[46:47], s[64:65] op_sel_hi:[1,0]
	v_lshlrev_b32_e32 v50, 16, v53
	v_cvt_pk_bf16_f32 v44, v46, v47
	v_lshlrev_b32_e32 v46, 16, v57
	v_and_b32_e32 v47, 0xffff0000, v57
	v_pk_fma_f32 v[46:47], v[98:99], v[46:47], v[68:69]
	v_and_b32_e32 v51, 0xffff0000, v53
	v_pk_fma_f32 v[46:47], v[100:101], v[50:51], v[46:47]
	v_add_f32_e32 v42, 1.0, v42
	v_pk_fma_f32 v[46:47], v[140:141], v[48:49], v[46:47]
	v_lshlrev_b32_e32 v48, 16, v45
	v_and_b32_e32 v49, 0xffff0000, v45
	v_pk_fma_f32 v[46:47], v[150:151], v[48:49], v[46:47]
	v_rcp_f32_e32 v153, v42
	v_mul_f32_e32 v45, 0xbfb8aa3b, v46
	v_exp_f32_e32 v45, v45
	v_lshlrev_b32_e32 v98, 2, v182
	v_pk_mul_f32 v[70:71], v[70:71], v[152:153]
	v_add_u32_e32 v66, s19, v98
	v_add_f32_e32 v45, 1.0, v45
	v_rcp_f32_e32 v48, v45
	v_mul_f32_e32 v45, 0xbfb8aa3b, v47
	v_exp_f32_e32 v45, v45
	v_pk_mul_f32 v[70:71], v[70:71], s[64:65] op_sel_hi:[1,0]
	v_add_u32_e32 v111, s33, v98
	v_cvt_pk_bf16_f32 v42, v70, v71
	v_add_f32_e32 v45, 1.0, v45
	v_rcp_f32_e32 v49, v45
	s_nop 0
	v_pk_mul_f32 v[46:47], v[46:47], v[48:49]
	s_nop 0
	v_pk_mul_f32 v[46:47], v[46:47], s[64:65] op_sel_hi:[1,0]
	v_lshlrev_b32_e32 v48, 16, v34
	v_cvt_pk_bf16_f32 v45, v46, v47
	v_lshlrev_b32_e32 v46, 16, v38
	v_and_b32_e32 v47, 0xffff0000, v38
	v_lshlrev_b32_e32 v38, 16, v39
	v_and_b32_e32 v39, 0xffff0000, v39
	v_pk_fma_f32 v[46:47], v[88:89], v[46:47], v[62:63]
	v_and_b32_e32 v49, 0xffff0000, v34
	v_pk_fma_f32 v[38:39], v[80:81], v[38:39], v[64:65]
	v_lshlrev_b32_e32 v34, 16, v35
	v_and_b32_e32 v35, 0xffff0000, v35
	v_pk_fma_f32 v[46:47], v[94:95], v[48:49], v[46:47]
	v_lshlrev_b32_e32 v48, 16, v30
	v_and_b32_e32 v49, 0xffff0000, v30
	v_pk_fma_f32 v[34:35], v[86:87], v[34:35], v[38:39]
	v_lshlrev_b32_e32 v30, 16, v31
	v_and_b32_e32 v31, 0xffff0000, v31
	v_pk_fma_f32 v[30:31], v[96:97], v[30:31], v[34:35]
	v_lshlrev_b32_e32 v34, 16, v27
	v_and_b32_e32 v35, 0xffff0000, v27
	v_pk_fma_f32 v[30:31], v[136:137], v[34:35], v[30:31]
	v_pk_fma_f32 v[46:47], v[104:105], v[48:49], v[46:47]
	v_mul_f32_e32 v27, 0xbfb8aa3b, v30
	v_exp_f32_e32 v27, v27
	v_lshlrev_b32_e32 v48, 16, v26
	v_and_b32_e32 v49, 0xffff0000, v26
	v_pk_fma_f32 v[46:47], v[144:145], v[48:49], v[46:47]
	v_add_f32_e32 v27, 1.0, v27
	v_rcp_f32_e32 v34, v27
	v_mul_f32_e32 v27, 0xbfb8aa3b, v31
	v_exp_f32_e32 v27, v27
	v_mul_f32_e32 v26, 0xbfb8aa3b, v46
	v_exp_f32_e32 v26, v26
	v_add_f32_e32 v27, 1.0, v27
	v_rcp_f32_e32 v35, v27
	v_add_f32_e32 v26, 1.0, v26
	v_rcp_f32_e32 v48, v26
	v_mul_f32_e32 v26, 0xbfb8aa3b, v47
	v_pk_mul_f32 v[30:31], v[30:31], v[34:35]
	v_lshlrev_b32_e32 v34, 16, v36
	v_pk_mul_f32 v[30:31], v[30:31], s[64:65] op_sel_hi:[1,0]
	v_and_b32_e32 v35, 0xffff0000, v36
	v_cvt_pk_bf16_f32 v27, v30, v31
	v_lshlrev_b32_e32 v30, 16, v40
	v_and_b32_e32 v31, 0xffff0000, v40
	v_pk_fma_f32 v[30:31], v[76:77], v[30:31], v[58:59]
	v_exp_f32_e32 v26, v26
	v_pk_fma_f32 v[30:31], v[82:83], v[34:35], v[30:31]
	v_lshlrev_b32_e32 v34, 16, v32
	v_and_b32_e32 v35, 0xffff0000, v32
	v_pk_fma_f32 v[30:31], v[90:91], v[34:35], v[30:31]
	v_lshlrev_b32_e32 v34, 16, v28
	v_and_b32_e32 v35, 0xffff0000, v28
	v_pk_fma_f32 v[30:31], v[102:103], v[34:35], v[30:31]
	v_lshlrev_b32_e32 v32, 16, v33
	v_mul_f32_e32 v28, 0xbfb8aa3b, v30
	v_exp_f32_e32 v28, v28
	v_and_b32_e32 v33, 0xffff0000, v33
	v_add_f32_e32 v26, 1.0, v26
	v_rcp_f32_e32 v49, v26
	v_add_f32_e32 v28, 1.0, v28
	v_rcp_f32_e32 v34, v28
	v_mul_f32_e32 v28, 0xbfb8aa3b, v31
	v_exp_f32_e32 v28, v28
	v_pk_mul_f32 v[46:47], v[46:47], v[48:49]
	v_add_f32_e32 v28, 1.0, v28
	v_rcp_f32_e32 v35, v28
	v_pk_mul_f32 v[46:47], v[46:47], s[64:65] op_sel_hi:[1,0]
	v_pk_mul_f32 v[30:31], v[30:31], v[34:35]
	s_nop 0
	v_pk_mul_f32 v[30:31], v[30:31], s[64:65] op_sel_hi:[1,0]
	v_lshlrev_b32_e32 v34, 16, v37
	v_cvt_pk_bf16_f32 v28, v30, v31
	v_lshlrev_b32_e32 v30, 16, v41
	v_and_b32_e32 v31, 0xffff0000, v41
	v_pk_fma_f32 v[30:31], v[74:75], v[30:31], v[60:61]
	v_and_b32_e32 v35, 0xffff0000, v37
	v_pk_fma_f32 v[30:31], v[78:79], v[34:35], v[30:31]
	v_cvt_pk_bf16_f32 v26, v46, v47
	v_pk_fma_f32 v[30:31], v[84:85], v[32:33], v[30:31]
	v_lshlrev_b32_e32 v32, 16, v29
	v_and_b32_e32 v33, 0xffff0000, v29
	v_pk_fma_f32 v[30:31], v[92:93], v[32:33], v[30:31]
	s_nop 0
	v_mul_f32_e32 v29, 0xbfb8aa3b, v30
	v_exp_f32_e32 v29, v29
	s_nop 0
	v_add_f32_e32 v29, 1.0, v29
	v_rcp_f32_e32 v32, v29
	v_mul_f32_e32 v29, 0xbfb8aa3b, v31
	v_exp_f32_e32 v29, v29
	s_nop 0
	v_add_f32_e32 v29, 1.0, v29
	v_rcp_f32_e32 v33, v29
	s_nop 0
	v_pk_mul_f32 v[30:31], v[30:31], v[32:33]
	s_nop 0
	v_pk_mul_f32 v[30:31], v[30:31], s[64:65] op_sel_hi:[1,0]
	s_nop 0
	v_cvt_pk_bf16_f32 v29, v30, v31
	ds_write_b128 v113, v[42:45] offset:32768
	ds_write_b128 v115, v[26:29] offset:32768
	v_ashrrev_i32_e32 v27, 1, v106
	v_lshl_add_u32 v26, v192, 13, s23
	v_and_b32_e32 v166, -16, v27
	v_add3_u32 v28, v26, v166, v196
	s_waitcnt vmcnt(1)
	ds_write_b16 v28, v22
	v_bitop3_b32 v28, v27, 16, -16 bitop3:0x6c
	v_add3_u32 v167, v26, v28, v196
	ds_write_b16_d16_hi v167, v22 offset:256
	v_bitop3_b32 v22, v27, 32, -16 bitop3:0x6c
	v_add3_u32 v168, v26, v22, v196
	v_bitop3_b32 v22, v27, 48, -16 bitop3:0x6c
	v_add3_u32 v169, v26, v22, v196
	v_bitop3_b32 v22, v27, 64, -16 bitop3:0x6c
	v_add3_u32 v170, v26, v22, v196
	v_bitop3_b32 v22, v27, s2, -16 bitop3:0x6c
	s_movk_i32 s2, 0x60
	v_add3_u32 v171, v26, v22, v196
	v_bitop3_b32 v22, v27, s2, -16 bitop3:0x6c
	s_movk_i32 s2, 0x70
	v_add3_u32 v172, v26, v22, v196
	v_bitop3_b32 v22, v27, s2, -16 bitop3:0x6c
	v_add3_u32 v173, v26, v22, v196
	v_bitop3_b32 v22, v27, s65, -16 bitop3:0x6c
	s_movk_i32 s2, 0x90
	v_add3_u32 v174, v26, v22, v196
	v_bitop3_b32 v22, v27, s2, -16 bitop3:0x6c
	v_add3_u32 v175, v26, v22, v196
	s_movk_i32 s2, 0xa0
	ds_write_b16 v168, v23 offset:512
	ds_write_b16_d16_hi v169, v23 offset:768
	ds_write_b16 v170, v24 offset:1024
	ds_write_b16_d16_hi v171, v24 offset:1280
	ds_write_b16 v172, v25 offset:1536
	ds_write_b16_d16_hi v173, v25 offset:1792
	s_waitcnt vmcnt(0)
	ds_write_b16 v174, v18 offset:2048
	ds_write_b16_d16_hi v175, v18 offset:2304
	v_bitop3_b32 v18, v27, s2, -16 bitop3:0x6c
	s_movk_i32 s2, 0xb0
	v_add3_u32 v176, v26, v18, v196
	v_bitop3_b32 v18, v27, s2, -16 bitop3:0x6c
	s_movk_i32 s2, 0xc0
	v_add3_u32 v177, v26, v18, v196
	v_bitop3_b32 v18, v27, s2, -16 bitop3:0x6c
	s_movk_i32 s2, 0xd0
	v_add3_u32 v178, v26, v18, v196
	v_bitop3_b32 v18, v27, s2, -16 bitop3:0x6c
	s_movk_i32 s2, 0xe0
	v_add3_u32 v179, v26, v18, v196
	v_bitop3_b32 v18, v27, s2, -16 bitop3:0x6c
	s_movk_i32 s2, 0xf0
	v_add3_u32 v180, v26, v18, v196
	v_bitop3_b32 v18, v27, s2, -16 bitop3:0x6c
	v_add3_u32 v181, v26, v18, v196
	ds_write_b16 v176, v19 offset:2560
	ds_write_b16_d16_hi v177, v19 offset:2816
	ds_write_b16 v178, v20 offset:3072
	ds_write_b16_d16_hi v179, v20 offset:3328
	ds_write_b16 v180, v21 offset:3584
	ds_write_b16_d16_hi v181, v21 offset:3840
	global_load_dwordx4 v[18:21], v[132:133], off offset:16
	global_load_dwordx4 v[34:37], v[132:133], off
	global_load_dwordx4 v[22:25], v[130:131], off offset:16
	global_load_dwordx4 v[38:41], v[130:131], off
	global_load_dwordx4 v[26:29], v[128:129], off offset:16
	global_load_dwordx4 v[42:45], v[128:129], off
	global_load_dwordx4 v[30:33], v[126:127], off offset:16
	global_load_dwordx4 v[46:49], v[126:127], off
	global_load_dwordx4 v[50:53], v[124:125], off offset:3120
	global_load_dwordx4 v[70:73], v[124:125], off offset:3104
	global_load_dwordx4 v[54:57], v[122:123], off offset:3120
	global_load_dwordx4 v[74:77], v[122:123], off offset:3104
	global_load_dwordx4 v[58:61], v[120:121], off offset:3120
	global_load_dwordx4 v[78:81], v[120:121], off offset:3104
	global_load_dwordx4 v[62:65], v[118:119], off offset:3120
	global_load_dwordx4 v[86:89], v[118:119], off offset:3104
	ds_read_b128 v[94:97], v66
	ds_read_b128 v[90:93], v66 offset:16
	ds_read_b128 v[82:85], v66 offset:32
	ds_read_b128 v[66:69], v66 offset:48
	ds_read_b128 v[98:101], v111
	ds_read_b128 v[102:105], v111 offset:16
	ds_read_b128 v[118:121], v111 offset:32
	ds_read_b128 v[130:133], v111 offset:48
	ds_read_b128 v[184:187], v111 offset:2096
	s_waitcnt lgkmcnt(4)
	v_pk_mul_f32 v[156:157], v[114:115], v[98:99] op_sel_hi:[0,1]
	s_waitcnt lgkmcnt(3)
	v_pk_mul_f32 v[128:129], v[114:115], v[104:105] op_sel_hi:[0,1]
	s_waitcnt lgkmcnt(2)
	v_pk_mul_f32 v[104:105], v[114:115], v[120:121] op_sel_hi:[0,1]
	v_pk_mul_f32 v[124:125], v[114:115], v[118:119] op_sel_hi:[0,1]
	ds_read_b128 v[118:121], v111 offset:1024
	s_waitcnt lgkmcnt(2)
	v_pk_mul_f32 v[98:99], v[114:115], v[132:133] op_sel_hi:[0,1]
	ds_read_b128 v[132:135], v111 offset:2048
	v_pk_mul_f32 v[148:149], v[114:115], v[100:101] op_sel_hi:[0,1]
	v_pk_mul_f32 v[100:101], v[114:115], v[130:131] op_sel_hi:[0,1]
	s_waitcnt lgkmcnt(1)
	v_pk_mul_f32 v[152:153], v[112:113], v[120:121] op_sel_hi:[0,1]
	v_pk_mul_f32 v[160:161], v[112:113], v[118:119] op_sel_hi:[0,1]
	ds_read_b128 v[118:121], v111 offset:1040
	s_waitcnt lgkmcnt(1)
	v_pk_mul_f32 v[198:199], v[110:111], v[134:135] op_sel_hi:[0,1]
	v_pk_mul_f32 v[200:201], v[110:111], v[132:133] op_sel_hi:[0,1]
	ds_read_b128 v[132:135], v111 offset:2064
	v_pk_mul_f32 v[138:139], v[114:115], v[102:103] op_sel_hi:[0,1]
	s_waitcnt lgkmcnt(1)
	v_pk_mul_f32 v[136:137], v[112:113], v[120:121] op_sel_hi:[0,1]
	v_pk_mul_f32 v[144:145], v[112:113], v[118:119] op_sel_hi:[0,1]
	ds_read_b128 v[118:121], v111 offset:1056
	s_waitcnt lgkmcnt(1)
	v_pk_mul_f32 v[150:151], v[110:111], v[134:135] op_sel_hi:[0,1]
	v_pk_mul_f32 v[158:159], v[110:111], v[132:133] op_sel_hi:[0,1]
	ds_read_b128 v[132:135], v111 offset:2080
	v_pk_mul_f32 v[126:127], v[110:111], v[184:185] op_sel_hi:[0,1]
	s_waitcnt lgkmcnt(1)
	v_pk_mul_f32 v[122:123], v[112:113], v[120:121] op_sel_hi:[0,1]
	v_pk_mul_f32 v[130:131], v[112:113], v[118:119] op_sel_hi:[0,1]
	ds_read_b128 v[118:121], v111 offset:1072
	s_waitcnt lgkmcnt(1)
	v_pk_mul_f32 v[142:143], v[110:111], v[132:133] op_sel_hi:[0,1]
	v_pk_mul_f32 v[134:135], v[110:111], v[134:135] op_sel_hi:[0,1]
	s_waitcnt lgkmcnt(0)
	v_pk_mul_f32 v[102:103], v[112:113], v[120:121] op_sel_hi:[0,1]
	v_pk_mul_f32 v[120:121], v[110:111], v[186:187] op_sel_hi:[0,1]
	ds_read_b128 v[184:187], v111 offset:3072
	v_pk_mul_f32 v[118:119], v[112:113], v[118:119] op_sel_hi:[0,1]
	s_waitcnt lgkmcnt(0)
	v_pk_mul_f32 v[202:203], v[0:1], v[186:187] op_sel_hi:[0,1]
	v_pk_mul_f32 v[204:205], v[0:1], v[184:185] op_sel_hi:[0,1]
	ds_read_b128 v[184:187], v111 offset:3088
	s_waitcnt lgkmcnt(0)
	v_pk_mul_f32 v[206:207], v[0:1], v[186:187] op_sel_hi:[0,1]
	v_pk_mul_f32 v[208:209], v[0:1], v[184:185] op_sel_hi:[0,1]
	ds_read_b128 v[184:187], v111 offset:3104
	s_waitcnt lgkmcnt(0)
	v_pk_mul_f32 v[146:147], v[0:1], v[186:187] op_sel_hi:[0,1]
	v_pk_mul_f32 v[154:155], v[0:1], v[184:185] op_sel_hi:[0,1]
	ds_read_b128 v[184:187], v111 offset:3120
	s_waitcnt lgkmcnt(0)
	v_pk_mul_f32 v[140:141], v[0:1], v[184:185] op_sel_hi:[0,1]
	v_pk_mul_f32 v[132:133], v[0:1], v[186:187] op_sel_hi:[0,1]
	s_waitcnt vmcnt(0)
	v_lshlrev_b32_e32 v184, 16, v86
	v_and_b32_e32 v185, 0xffff0000, v86
	v_pk_fma_f32 v[94:95], v[156:157], v[184:185], v[94:95]
	v_lshlrev_b32_e32 v156, 16, v78
	v_and_b32_e32 v157, 0xffff0000, v78
	v_pk_fma_f32 v[94:95], v[160:161], v[156:157], v[94:95]
	v_lshlrev_b32_e32 v156, 16, v74
	v_and_b32_e32 v157, 0xffff0000, v74
	v_pk_fma_f32 v[94:95], v[200:201], v[156:157], v[94:95]
	v_lshlrev_b32_e32 v156, 16, v70
	v_and_b32_e32 v157, 0xffff0000, v70
	v_pk_fma_f32 v[94:95], v[204:205], v[156:157], v[94:95]
	v_lshlrev_b32_e32 v86, 16, v87
	v_mul_f32_e32 v70, 0xbfb8aa3b, v94
	v_exp_f32_e32 v70, v70
	v_and_b32_e32 v87, 0xffff0000, v87
	v_pk_fma_f32 v[86:87], v[148:149], v[86:87], v[96:97]
	v_lshlrev_b32_e32 v78, 16, v79
	v_add_f32_e32 v70, 1.0, v70
	v_rcp_f32_e32 v156, v70
	v_mul_f32_e32 v70, 0xbfb8aa3b, v95
	v_exp_f32_e32 v70, v70
	v_and_b32_e32 v79, 0xffff0000, v79
	v_pk_fma_f32 v[78:79], v[152:153], v[78:79], v[86:87]
	v_lshlrev_b32_e32 v74, 16, v75
	v_add_f32_e32 v70, 1.0, v70
	v_and_b32_e32 v75, 0xffff0000, v75
	v_rcp_f32_e32 v157, v70
	v_pk_fma_f32 v[74:75], v[198:199], v[74:75], v[78:79]
	v_lshlrev_b32_e32 v70, 16, v71
	v_and_b32_e32 v71, 0xffff0000, v71
	v_pk_fma_f32 v[70:71], v[202:203], v[70:71], v[74:75]
	v_lshlrev_b32_e32 v78, 16, v80
	v_mul_f32_e32 v74, 0xbfb8aa3b, v70
	v_mul_f32_e32 v75, 0xbfb8aa3b, v71
	v_exp_f32_e32 v74, v74
	v_exp_f32_e32 v75, v75
	v_and_b32_e32 v79, 0xffff0000, v80
	v_lshlrev_b32_e32 v80, 16, v81
	v_add_f32_e32 v74, 1.0, v74
	v_add_f32_e32 v75, 1.0, v75
	v_rcp_f32_e32 v74, v74
	v_rcp_f32_e32 v75, v75
	v_and_b32_e32 v81, 0xffff0000, v81
	v_pk_mul_f32 v[94:95], v[94:95], v[156:157]
	v_pk_mul_f32 v[70:71], v[70:71], v[74:75]
	v_lshlrev_b32_e32 v74, 16, v88
	v_and_b32_e32 v75, 0xffff0000, v88
	v_pk_fma_f32 v[74:75], v[138:139], v[74:75], v[90:91]
	s_nop 0
	v_pk_fma_f32 v[74:75], v[144:145], v[78:79], v[74:75]
	v_lshlrev_b32_e32 v78, 16, v76
	v_and_b32_e32 v79, 0xffff0000, v76
	v_pk_fma_f32 v[74:75], v[158:159], v[78:79], v[74:75]
	v_lshlrev_b32_e32 v78, 16, v72
	v_and_b32_e32 v79, 0xffff0000, v72
	v_pk_fma_f32 v[74:75], v[208:209], v[78:79], v[74:75]
	v_lshlrev_b32_e32 v76, 16, v77
	v_mul_f32_e32 v72, 0xbfb8aa3b, v74
	v_exp_f32_e32 v72, v72
	v_and_b32_e32 v77, 0xffff0000, v77
	v_add_f32_e32 v72, 1.0, v72
	v_rcp_f32_e32 v78, v72
	v_mul_f32_e32 v72, 0xbfb8aa3b, v75
	v_exp_f32_e32 v72, v72
	s_nop 0
	v_add_f32_e32 v72, 1.0, v72
	v_rcp_f32_e32 v79, v72
	v_lshlrev_b32_e32 v72, 16, v73
	v_and_b32_e32 v73, 0xffff0000, v73
	v_pk_mul_f32 v[74:75], v[74:75], v[78:79]
	v_lshlrev_b32_e32 v78, 16, v89
	v_and_b32_e32 v79, 0xffff0000, v89
	v_pk_fma_f32 v[78:79], v[128:129], v[78:79], v[92:93]
	s_nop 0
	v_pk_fma_f32 v[78:79], v[136:137], v[80:81], v[78:79]
	s_nop 0
	v_pk_fma_f32 v[76:77], v[150:151], v[76:77], v[78:79]
	v_lshlrev_b32_e32 v78, 16, v58
	v_pk_fma_f32 v[72:73], v[206:207], v[72:73], v[76:77]
	v_and_b32_e32 v79, 0xffff0000, v58
	v_mul_f32_e32 v76, 0xbfb8aa3b, v72
	v_mul_f32_e32 v77, 0xbfb8aa3b, v73
	v_exp_f32_e32 v76, v76
	v_exp_f32_e32 v77, v77
	v_lshlrev_b32_e32 v58, 16, v59
	v_and_b32_e32 v59, 0xffff0000, v59
	v_add_f32_e32 v76, 1.0, v76
	v_add_f32_e32 v77, 1.0, v77
	v_rcp_f32_e32 v76, v76
	v_rcp_f32_e32 v77, v77
	s_nop 0
	v_pk_mul_f32 v[72:73], v[72:73], v[76:77]
	v_lshlrev_b32_e32 v76, 16, v62
	v_and_b32_e32 v77, 0xffff0000, v62
	v_pk_fma_f32 v[76:77], v[124:125], v[76:77], v[82:83]
	v_lshlrev_b32_e32 v62, 16, v63
	v_pk_fma_f32 v[76:77], v[130:131], v[78:79], v[76:77]
	v_lshlrev_b32_e32 v78, 16, v54
	v_and_b32_e32 v79, 0xffff0000, v54
	v_pk_fma_f32 v[76:77], v[142:143], v[78:79], v[76:77]
	v_lshlrev_b32_e32 v78, 16, v50
	v_and_b32_e32 v79, 0xffff0000, v50
	v_pk_fma_f32 v[76:77], v[154:155], v[78:79], v[76:77]
	v_and_b32_e32 v63, 0xffff0000, v63
	v_mul_f32_e32 v50, 0xbfb8aa3b, v76
	v_exp_f32_e32 v50, v50
	v_pk_fma_f32 v[62:63], v[104:105], v[62:63], v[84:85]
	v_lshlrev_b32_e32 v54, 16, v55
	v_pk_fma_f32 v[58:59], v[122:123], v[58:59], v[62:63]
	v_add_f32_e32 v50, 1.0, v50
	v_rcp_f32_e32 v78, v50
	v_mul_f32_e32 v50, 0xbfb8aa3b, v77
	v_exp_f32_e32 v50, v50
	v_and_b32_e32 v55, 0xffff0000, v55
	v_pk_fma_f32 v[54:55], v[134:135], v[54:55], v[58:59]
	v_lshlrev_b32_e32 v58, 16, v60
	v_add_f32_e32 v50, 1.0, v50
	v_rcp_f32_e32 v79, v50
	v_lshlrev_b32_e32 v50, 16, v51
	v_and_b32_e32 v51, 0xffff0000, v51
	v_pk_fma_f32 v[50:51], v[146:147], v[50:51], v[54:55]
	v_and_b32_e32 v59, 0xffff0000, v60
	v_mul_f32_e32 v54, 0xbfb8aa3b, v50
	v_mul_f32_e32 v55, 0xbfb8aa3b, v51
	v_exp_f32_e32 v54, v54
	v_exp_f32_e32 v55, v55
	v_lshlrev_b32_e32 v60, 16, v61
	v_and_b32_e32 v61, 0xffff0000, v61
	v_add_f32_e32 v54, 1.0, v54
	v_add_f32_e32 v55, 1.0, v55
	v_rcp_f32_e32 v54, v54
	v_rcp_f32_e32 v55, v55
	v_pk_mul_f32 v[76:77], v[76:77], v[78:79]
	v_pk_mul_f32 v[50:51], v[50:51], v[54:55]
	v_lshlrev_b32_e32 v54, 16, v64
	v_and_b32_e32 v55, 0xffff0000, v64
	v_pk_fma_f32 v[54:55], v[100:101], v[54:55], v[66:67]
	v_lshrrev_b32_e32 v66, 3, v182
	v_pk_fma_f32 v[54:55], v[118:119], v[58:59], v[54:55]
	v_lshlrev_b32_e32 v58, 16, v56
	v_and_b32_e32 v59, 0xffff0000, v56
	v_pk_fma_f32 v[54:55], v[126:127], v[58:59], v[54:55]
	v_lshlrev_b32_e32 v58, 16, v52
	v_and_b32_e32 v59, 0xffff0000, v52
	v_pk_fma_f32 v[54:55], v[140:141], v[58:59], v[54:55]
	v_lshlrev_b32_e32 v56, 16, v57
	v_mul_f32_e32 v52, 0xbfb8aa3b, v54
	v_exp_f32_e32 v52, v52
	v_and_b32_e32 v57, 0xffff0000, v57
	v_cvt_pk_bf16_f32 v63, v50, v51
	v_bitop3_b32 v50, v66, v107, 15 bitop3:0x78
	v_add_f32_e32 v52, 1.0, v52
	v_rcp_f32_e32 v58, v52
	v_mul_f32_e32 v52, 0xbfb8aa3b, v55
	v_exp_f32_e32 v52, v52
	v_lshl_or_b32 v50, v50, 4, v194
	v_cvt_pk_bf16_f32 v62, v76, v77
	v_add_f32_e32 v52, 1.0, v52
	v_rcp_f32_e32 v59, v52
	v_lshlrev_b32_e32 v52, 16, v53
	v_and_b32_e32 v53, 0xffff0000, v53
	v_pk_mul_f32 v[54:55], v[54:55], v[58:59]
	v_lshlrev_b32_e32 v58, 16, v65
	v_and_b32_e32 v59, 0xffff0000, v65
	v_pk_fma_f32 v[58:59], v[98:99], v[58:59], v[68:69]
	v_cvt_pk_bf16_f32 v64, v54, v55
	v_pk_fma_f32 v[58:59], v[102:103], v[60:61], v[58:59]
	v_cvt_pk_bf16_f32 v60, v74, v75
	v_pk_fma_f32 v[56:57], v[120:121], v[56:57], v[58:59]
	v_cvt_pk_bf16_f32 v58, v94, v95
	v_pk_fma_f32 v[52:53], v[132:133], v[52:53], v[56:57]
	v_cvt_pk_bf16_f32 v59, v70, v71
	v_mul_f32_e32 v56, 0xbfb8aa3b, v52
	v_mul_f32_e32 v57, 0xbfb8aa3b, v53
	v_exp_f32_e32 v56, v56
	v_exp_f32_e32 v57, v57
	v_cvt_pk_bf16_f32 v61, v72, v73
	v_add_u32_e32 v132, 0, v50
	v_add_f32_e32 v56, 1.0, v56
	v_add_f32_e32 v57, 1.0, v57
	v_rcp_f32_e32 v56, v56
	v_rcp_f32_e32 v57, v57
	v_or_b32_e32 v74, 0x240, v195
	v_add_u32_e32 v102, s33, v74
	v_pk_mul_f32 v[52:53], v[52:53], v[56:57]
	s_nop 0
	v_cvt_pk_bf16_f32 v65, v52, v53
	global_load_dwordx4 v[54:57], v[116:117], off offset:32
	global_load_dwordx4 v[50:53], v[116:117], off offset:48
	ds_write_b128 v132, v[58:61]
	v_bitop3_b32 v58, v66, v193, 1 bitop3:0x36
	v_lshlrev_b32_e32 v58, 4, v58
	v_add3_u32 v133, v58, v194, 0
	ds_write_b128 v133, v[62:65]
	v_add_u32_e32 v58, s19, v74
	ds_read_b128 v[70:73], v58
	ds_read_b128 v[66:69], v58 offset:16
	ds_read_b128 v[62:65], v58 offset:32
	ds_read_b128 v[58:61], v58 offset:48
	ds_read_b128 v[74:77], v102
	ds_read_b128 v[78:81], v102 offset:16
	ds_read_b128 v[82:85], v102 offset:32
	ds_read_b128 v[90:93], v102 offset:48
	ds_read_b128 v[134:137], v102 offset:3072
	s_waitcnt lgkmcnt(4)
	v_pk_mul_f32 v[118:119], v[114:115], v[76:77] op_sel_hi:[0,1]
	s_waitcnt lgkmcnt(3)
	v_pk_mul_f32 v[98:99], v[114:115], v[80:81] op_sel_hi:[0,1]
	s_waitcnt lgkmcnt(2)
	v_pk_mul_f32 v[80:81], v[114:115], v[84:85] op_sel_hi:[0,1]
	v_pk_mul_f32 v[88:89], v[114:115], v[82:83] op_sel_hi:[0,1]
	ds_read_b128 v[82:85], v102 offset:1024
	v_pk_mul_f32 v[128:129], v[114:115], v[74:75] op_sel_hi:[0,1]
	s_waitcnt lgkmcnt(2)
	v_pk_mul_f32 v[74:75], v[114:115], v[92:93] op_sel_hi:[0,1]
	v_pk_mul_f32 v[76:77], v[114:115], v[90:91] op_sel_hi:[0,1]
	ds_read_b128 v[90:93], v102 offset:2048
	s_waitcnt lgkmcnt(1)
	v_pk_mul_f32 v[122:123], v[112:113], v[84:85] op_sel_hi:[0,1]
	v_pk_mul_f32 v[130:131], v[112:113], v[82:83] op_sel_hi:[0,1]
	ds_read_b128 v[82:85], v102 offset:1040
	v_pk_mul_f32 v[116:117], v[114:115], v[78:79] op_sel_hi:[0,1]
	s_waitcnt lgkmcnt(1)
	v_pk_mul_f32 v[138:139], v[110:111], v[92:93] op_sel_hi:[0,1]
	v_pk_mul_f32 v[140:141], v[110:111], v[90:91] op_sel_hi:[0,1]
	ds_read_b128 v[90:93], v102 offset:2064
	s_waitcnt lgkmcnt(1)
	v_pk_mul_f32 v[100:101], v[112:113], v[84:85] op_sel_hi:[0,1]
	v_pk_mul_f32 v[114:115], v[112:113], v[82:83] op_sel_hi:[0,1]
	ds_read_b128 v[82:85], v102 offset:1056
	v_pk_mul_f32 v[142:143], v[0:1], v[136:137] op_sel_hi:[0,1]
	s_waitcnt lgkmcnt(1)
	v_pk_mul_f32 v[124:125], v[110:111], v[90:91] op_sel_hi:[0,1]
	v_pk_mul_f32 v[144:145], v[0:1], v[134:135] op_sel_hi:[0,1]
	ds_read_b128 v[134:137], v102 offset:3088
	s_waitcnt lgkmcnt(1)
	v_pk_mul_f32 v[86:87], v[112:113], v[84:85] op_sel_hi:[0,1]
	v_pk_mul_f32 v[94:95], v[112:113], v[82:83] op_sel_hi:[0,1]
	ds_read_b128 v[82:85], v102 offset:1072
	s_waitcnt lgkmcnt(1)
	v_pk_mul_f32 v[126:127], v[0:1], v[136:137] op_sel_hi:[0,1]
	v_pk_mul_f32 v[146:147], v[0:1], v[134:135] op_sel_hi:[0,1]
	ds_read_b128 v[134:137], v102 offset:3104
	s_waitcnt lgkmcnt(1)
	v_pk_mul_f32 v[78:79], v[112:113], v[84:85] op_sel_hi:[0,1]
	v_pk_mul_f32 v[82:83], v[112:113], v[82:83] op_sel_hi:[0,1]
	v_pk_mul_f32 v[112:113], v[110:111], v[92:93] op_sel_hi:[0,1]
	ds_read_b128 v[90:93], v102 offset:2080
	s_waitcnt lgkmcnt(1)
	v_pk_mul_f32 v[120:121], v[0:1], v[134:135] op_sel_hi:[0,1]
	s_waitcnt lgkmcnt(0)
	v_pk_mul_f32 v[96:97], v[110:111], v[92:93] op_sel_hi:[0,1]
	v_pk_mul_f32 v[104:105], v[110:111], v[90:91] op_sel_hi:[0,1]
	ds_read_b128 v[90:93], v102 offset:2096
	s_waitcnt lgkmcnt(0)
	v_pk_mul_f32 v[84:85], v[110:111], v[92:93] op_sel_hi:[0,1]
	v_pk_mul_f32 v[90:91], v[110:111], v[90:91] op_sel_hi:[0,1]
	v_pk_mul_f32 v[110:111], v[0:1], v[136:137] op_sel_hi:[0,1]
	ds_read_b128 v[134:137], v102 offset:3120
	s_waitcnt lgkmcnt(0)
	v_pk_mul_f32 v[102:103], v[0:1], v[134:135] op_sel_hi:[0,1]
	v_lshlrev_b32_e32 v134, 16, v46
	v_and_b32_e32 v135, 0xffff0000, v46
	v_pk_fma_f32 v[70:71], v[128:129], v[134:135], v[70:71]
	v_lshlrev_b32_e32 v128, 16, v42
	v_and_b32_e32 v129, 0xffff0000, v42
	v_pk_fma_f32 v[70:71], v[130:131], v[128:129], v[70:71]
	v_lshlrev_b32_e32 v128, 16, v38
	v_and_b32_e32 v129, 0xffff0000, v38
	v_pk_fma_f32 v[70:71], v[140:141], v[128:129], v[70:71]
	v_lshlrev_b32_e32 v128, 16, v34
	v_and_b32_e32 v129, 0xffff0000, v34
	v_pk_fma_f32 v[70:71], v[144:145], v[128:129], v[70:71]
	v_pk_mul_f32 v[92:93], v[0:1], v[136:137] op_sel_hi:[0,1]
	v_mul_f32_e32 v0, 0xbfb8aa3b, v70
	v_exp_f32_e32 v0, v0
	v_lshlrev_b32_e32 v46, 16, v47
	v_and_b32_e32 v47, 0xffff0000, v47
	v_pk_fma_f32 v[46:47], v[118:119], v[46:47], v[72:73]
	v_add_f32_e32 v0, 1.0, v0
	v_rcp_f32_e32 v128, v0
	v_mul_f32_e32 v0, 0xbfb8aa3b, v71
	v_exp_f32_e32 v0, v0
	v_lshlrev_b32_e32 v42, 16, v43
	v_and_b32_e32 v43, 0xffff0000, v43
	v_pk_fma_f32 v[42:43], v[122:123], v[42:43], v[46:47]
	v_lshlrev_b32_e32 v38, 16, v39
	v_and_b32_e32 v39, 0xffff0000, v39
	v_pk_fma_f32 v[38:39], v[138:139], v[38:39], v[42:43]
	v_lshlrev_b32_e32 v42, 16, v35
	v_and_b32_e32 v43, 0xffff0000, v35
	v_add_f32_e32 v0, 1.0, v0
	v_pk_fma_f32 v[38:39], v[142:143], v[42:43], v[38:39]
	v_rcp_f32_e32 v129, v0
	v_mul_f32_e32 v0, 0xbfb8aa3b, v38
	v_exp_f32_e32 v0, v0
	v_pk_mul_f32 v[70:71], v[70:71], v[128:129]
	s_nop 0
	v_pk_mul_f32 v[70:71], v[70:71], s[64:65] op_sel_hi:[1,0]
	v_add_f32_e32 v0, 1.0, v0
	v_rcp_f32_e32 v42, v0
	v_mul_f32_e32 v0, 0xbfb8aa3b, v39
	v_exp_f32_e32 v0, v0
	v_cvt_pk_bf16_f32 v34, v70, v71
	v_add_f32_e32 v0, 1.0, v0
	v_rcp_f32_e32 v43, v0
	s_nop 0
	v_pk_mul_f32 v[38:39], v[38:39], v[42:43]
	s_nop 0
	v_pk_mul_f32 v[38:39], v[38:39], s[64:65] op_sel_hi:[1,0]
	v_lshlrev_b32_e32 v42, 16, v44
	v_cvt_pk_bf16_f32 v35, v38, v39
	v_lshlrev_b32_e32 v38, 16, v48
	v_and_b32_e32 v39, 0xffff0000, v48
	v_pk_fma_f32 v[38:39], v[116:117], v[38:39], v[66:67]
	v_and_b32_e32 v43, 0xffff0000, v44
	v_pk_fma_f32 v[38:39], v[114:115], v[42:43], v[38:39]
	v_lshlrev_b32_e32 v42, 16, v40
	v_and_b32_e32 v43, 0xffff0000, v40
	v_pk_fma_f32 v[38:39], v[124:125], v[42:43], v[38:39]
	v_lshlrev_b32_e32 v42, 16, v36
	v_and_b32_e32 v43, 0xffff0000, v36
	v_pk_fma_f32 v[38:39], v[146:147], v[42:43], v[38:39]
	v_lshlrev_b32_e32 v40, 16, v41
	v_mul_f32_e32 v0, 0xbfb8aa3b, v38
	v_exp_f32_e32 v0, v0
	v_and_b32_e32 v41, 0xffff0000, v41
	v_add_f32_e32 v0, 1.0, v0
	v_rcp_f32_e32 v42, v0
	v_mul_f32_e32 v0, 0xbfb8aa3b, v39
	v_exp_f32_e32 v0, v0
	s_nop 0
	v_add_f32_e32 v0, 1.0, v0
	v_rcp_f32_e32 v43, v0
	s_nop 0
	v_pk_mul_f32 v[38:39], v[38:39], v[42:43]
	s_nop 0
	v_pk_mul_f32 v[38:39], v[38:39], s[64:65] op_sel_hi:[1,0]
	v_lshlrev_b32_e32 v42, 16, v45
	v_cvt_pk_bf16_f32 v36, v38, v39
	v_lshlrev_b32_e32 v38, 16, v49
	v_and_b32_e32 v39, 0xffff0000, v49
	v_pk_fma_f32 v[38:39], v[98:99], v[38:39], v[68:69]
	v_and_b32_e32 v43, 0xffff0000, v45
	v_pk_fma_f32 v[38:39], v[100:101], v[42:43], v[38:39]
	s_nop 0
	v_pk_fma_f32 v[38:39], v[112:113], v[40:41], v[38:39]
	v_lshlrev_b32_e32 v40, 16, v37
	v_and_b32_e32 v41, 0xffff0000, v37
	v_pk_fma_f32 v[38:39], v[126:127], v[40:41], v[38:39]
	s_nop 0
	v_mul_f32_e32 v0, 0xbfb8aa3b, v38
	v_exp_f32_e32 v0, v0
	s_nop 0
	v_add_f32_e32 v0, 1.0, v0
	v_rcp_f32_e32 v40, v0
	v_mul_f32_e32 v0, 0xbfb8aa3b, v39
	v_exp_f32_e32 v0, v0
	s_nop 0
	v_add_f32_e32 v0, 1.0, v0
	v_rcp_f32_e32 v41, v0
	s_nop 0
	v_pk_mul_f32 v[38:39], v[38:39], v[40:41]
	s_nop 0
	v_pk_mul_f32 v[38:39], v[38:39], s[64:65] op_sel_hi:[1,0]
	v_lshlrev_b32_e32 v40, 16, v26
	v_cvt_pk_bf16_f32 v37, v38, v39
	v_lshlrev_b32_e32 v38, 16, v30
	v_and_b32_e32 v39, 0xffff0000, v30
	v_pk_fma_f32 v[38:39], v[88:89], v[38:39], v[62:63]
	v_and_b32_e32 v41, 0xffff0000, v26
	v_pk_fma_f32 v[38:39], v[94:95], v[40:41], v[38:39]
	v_lshlrev_b32_e32 v40, 16, v22
	v_and_b32_e32 v41, 0xffff0000, v22
	v_pk_fma_f32 v[38:39], v[104:105], v[40:41], v[38:39]
	v_lshlrev_b32_e32 v40, 16, v18
	v_and_b32_e32 v41, 0xffff0000, v18
	v_pk_fma_f32 v[38:39], v[120:121], v[40:41], v[38:39]
	v_lshlrev_b32_e32 v30, 16, v31
	v_mul_f32_e32 v0, 0xbfb8aa3b, v38
	v_exp_f32_e32 v0, v0
	v_and_b32_e32 v31, 0xffff0000, v31
	v_pk_fma_f32 v[30:31], v[80:81], v[30:31], v[64:65]
	v_lshlrev_b32_e32 v26, 16, v27
	v_add_f32_e32 v0, 1.0, v0
	v_rcp_f32_e32 v40, v0
	v_mul_f32_e32 v0, 0xbfb8aa3b, v39
	v_exp_f32_e32 v0, v0
	v_and_b32_e32 v27, 0xffff0000, v27
	v_pk_fma_f32 v[26:27], v[86:87], v[26:27], v[30:31]
	v_lshlrev_b32_e32 v22, 16, v23
	v_and_b32_e32 v23, 0xffff0000, v23
	v_pk_fma_f32 v[22:23], v[96:97], v[22:23], v[26:27]
	v_lshlrev_b32_e32 v26, 16, v19
	v_and_b32_e32 v27, 0xffff0000, v19
	v_add_f32_e32 v0, 1.0, v0
	v_pk_fma_f32 v[22:23], v[110:111], v[26:27], v[22:23]
	v_rcp_f32_e32 v41, v0
	v_mul_f32_e32 v0, 0xbfb8aa3b, v22
	v_exp_f32_e32 v0, v0
	v_pk_mul_f32 v[38:39], v[38:39], v[40:41]
	s_nop 0
	v_pk_mul_f32 v[38:39], v[38:39], s[64:65] op_sel_hi:[1,0]
	v_add_f32_e32 v0, 1.0, v0
	v_rcp_f32_e32 v26, v0
	v_mul_f32_e32 v0, 0xbfb8aa3b, v23
	v_exp_f32_e32 v0, v0
	v_cvt_pk_bf16_f32 v18, v38, v39
	v_add_f32_e32 v0, 1.0, v0
	v_rcp_f32_e32 v27, v0
	s_nop 0
	v_pk_mul_f32 v[22:23], v[22:23], v[26:27]
	s_nop 0
	v_pk_mul_f32 v[22:23], v[22:23], s[64:65] op_sel_hi:[1,0]
	v_lshlrev_b32_e32 v26, 16, v28
	v_cvt_pk_bf16_f32 v19, v22, v23
	v_lshlrev_b32_e32 v22, 16, v32
	v_and_b32_e32 v23, 0xffff0000, v32
	v_pk_fma_f32 v[22:23], v[76:77], v[22:23], v[58:59]
	v_and_b32_e32 v27, 0xffff0000, v28
	v_pk_fma_f32 v[22:23], v[82:83], v[26:27], v[22:23]
	v_lshlrev_b32_e32 v26, 16, v24
	v_and_b32_e32 v27, 0xffff0000, v24
	v_pk_fma_f32 v[22:23], v[90:91], v[26:27], v[22:23]
	v_lshlrev_b32_e32 v26, 16, v20
	v_and_b32_e32 v27, 0xffff0000, v20
	v_pk_fma_f32 v[22:23], v[102:103], v[26:27], v[22:23]
	v_lshlrev_b32_e32 v24, 16, v25
	v_mul_f32_e32 v0, 0xbfb8aa3b, v22
	v_exp_f32_e32 v0, v0
	v_and_b32_e32 v25, 0xffff0000, v25
	v_add_f32_e32 v0, 1.0, v0
	v_rcp_f32_e32 v26, v0
	v_mul_f32_e32 v0, 0xbfb8aa3b, v23
	v_exp_f32_e32 v0, v0
	s_nop 0
	v_add_f32_e32 v0, 1.0, v0
	v_rcp_f32_e32 v27, v0
	s_nop 0
	v_pk_mul_f32 v[22:23], v[22:23], v[26:27]
	s_nop 0
	v_pk_mul_f32 v[22:23], v[22:23], s[64:65] op_sel_hi:[1,0]
	v_lshlrev_b32_e32 v26, 16, v29
	v_cvt_pk_bf16_f32 v20, v22, v23
	v_lshlrev_b32_e32 v22, 16, v33
	v_and_b32_e32 v23, 0xffff0000, v33
	v_pk_fma_f32 v[22:23], v[74:75], v[22:23], v[60:61]
	v_and_b32_e32 v27, 0xffff0000, v29
	v_pk_fma_f32 v[22:23], v[78:79], v[26:27], v[22:23]
	s_nop 0
	v_pk_fma_f32 v[22:23], v[84:85], v[24:25], v[22:23]
	v_lshlrev_b32_e32 v24, 16, v21
	v_and_b32_e32 v25, 0xffff0000, v21
	v_pk_fma_f32 v[22:23], v[92:93], v[24:25], v[22:23]
	s_nop 0
	v_mul_f32_e32 v0, 0xbfb8aa3b, v22
	v_exp_f32_e32 v0, v0
	s_nop 0
	v_add_f32_e32 v0, 1.0, v0
	v_rcp_f32_e32 v24, v0
	v_mul_f32_e32 v0, 0xbfb8aa3b, v23
	v_exp_f32_e32 v0, v0
	s_nop 0
	v_add_f32_e32 v0, 1.0, v0
	v_rcp_f32_e32 v25, v0
	v_lshl_add_u32 v0, v182, 8, s23
	v_add3_u32 v0, v0, v166, v196
	v_pk_mul_f32 v[22:23], v[22:23], v[24:25]
	s_nop 0
	v_pk_mul_f32 v[22:23], v[22:23], s[64:65] op_sel_hi:[1,0]
	s_nop 0
	v_cvt_pk_bf16_f32 v21, v22, v23
	ds_write_b128 v132, v[34:37] offset:32768
	ds_write_b128 v133, v[18:21] offset:32768
	s_waitcnt vmcnt(1)
	ds_write_b16 v0, v54
	ds_write_b16_d16_hi v167, v54 offset:4352
	ds_write_b16 v168, v55 offset:4608
	ds_write_b16_d16_hi v169, v55 offset:4864
	ds_write_b16 v170, v56 offset:5120
	ds_write_b16_d16_hi v171, v56 offset:5376
	ds_write_b16 v172, v57 offset:5632
	ds_write_b16_d16_hi v173, v57 offset:5888
	s_waitcnt vmcnt(0)
	ds_write_b16 v174, v50 offset:6144
	ds_write_b16_d16_hi v175, v50 offset:6400
	ds_write_b16 v176, v51 offset:6656
	ds_write_b16_d16_hi v177, v51 offset:6912
	ds_write_b16 v178, v52 offset:7168
	ds_write_b16_d16_hi v179, v52 offset:7424
	ds_write_b16 v180, v53 offset:7680
	ds_write_b16_d16_hi v181, v53 offset:7936
	v_ashrrev_i32_e32 v0, 4, v106
	v_lshlrev_b32_e32 v18, 8, v0
	v_xor_b32_e32 v0, v0, v106
	v_lshlrev_b32_e32 v0, 4, v0
	v_and_b32_e32 v0, 0xf0, v0
	v_add3_u32 v0, s36, v0, v18
	ds_write_b128 v0, v[2:5]
	v_add_u32_e32 v0, 0x200, v106
	v_ashrrev_i32_e32 v0, 4, v0
	v_lshlrev_b32_e32 v2, 8, v0
	v_xor_b32_e32 v0, v0, v106
	v_lshlrev_b32_e32 v0, 4, v0
	v_and_b32_e32 v0, 0xf0, v0
	v_add3_u32 v0, s36, v0, v2
	ds_write_b128 v0, v[10:13]
	v_add_u32_e32 v0, 0x400, v106
	v_ashrrev_i32_e32 v0, 4, v0
	v_lshlrev_b32_e32 v2, 8, v0
	v_xor_b32_e32 v0, v0, v106
	v_lshlrev_b32_e32 v0, 4, v0
	v_and_b32_e32 v0, 0xf0, v0
	v_add3_u32 v0, s36, v0, v2
	ds_write_b128 v0, v[6:9]
	v_add_u32_e32 v0, 0x600, v106
	v_ashrrev_i32_e32 v0, 4, v0
	v_lshlrev_b32_e32 v2, 8, v0
	v_xor_b32_e32 v0, v0, v106
	v_lshlrev_b32_e32 v0, 4, v0
	v_and_b32_e32 v0, 0xf0, v0
	v_add3_u32 v0, s36, v0, v2
	ds_write_b128 v0, v[14:17]
	v_add_u32_e32 v0, 0, v194
	v_add_u32_e32 v2, v0, v165
	s_waitcnt lgkmcnt(0)
	s_barrier
	ds_read_b128 v[2:5], v2
	v_add_u32_e32 v10, s57, v195
	ds_read_b128 v[6:9], v10
	ds_read_b128 v[10:13], v10 offset:16
	v_lshlrev_b32_e32 v56, 2, v191
	s_waitcnt lgkmcnt(2)
	v_lshlrev_b32_e32 v14, 16, v2
	v_and_b32_e32 v2, 0xffff0000, v2
	s_waitcnt lgkmcnt(1)
	v_mul_f32_e32 v2, v7, v2
	v_fmac_f32_e32 v2, v6, v14
	v_lshlrev_b32_e32 v6, 16, v3
	v_fmac_f32_e32 v2, v8, v6
	v_and_b32_e32 v3, 0xffff0000, v3
	v_fmac_f32_e32 v2, v9, v3
	v_lshlrev_b32_e32 v3, 16, v4
	s_waitcnt lgkmcnt(0)
	v_fmac_f32_e32 v2, v10, v3
	v_and_b32_e32 v3, 0xffff0000, v4
	v_fmac_f32_e32 v2, v11, v3
	v_lshlrev_b32_e32 v3, 16, v5
	v_fmac_f32_e32 v2, v12, v3
	v_and_b32_e32 v3, 0xffff0000, v5
	v_fmac_f32_e32 v2, v13, v3
	v_add_f32_e32 v14, 0, v2
	v_add_u32_e32 v2, v0, v164
	ds_read_b128 v[2:5], v2
	v_lshl_add_u32 v10, v163, 5, s57
	ds_read_b128 v[6:9], v10
	ds_read_b128 v[10:13], v10 offset:16
	s_waitcnt lgkmcnt(2)
	v_lshlrev_b32_e32 v15, 16, v2
	v_and_b32_e32 v2, 0xffff0000, v2
	s_waitcnt lgkmcnt(1)
	v_mul_f32_e32 v2, v7, v2
	v_fmac_f32_e32 v2, v6, v15
	v_lshlrev_b32_e32 v6, 16, v3
	v_fmac_f32_e32 v2, v8, v6
	v_and_b32_e32 v3, 0xffff0000, v3
	v_fmac_f32_e32 v2, v9, v3
	v_lshlrev_b32_e32 v3, 16, v4
	s_waitcnt lgkmcnt(0)
	v_fmac_f32_e32 v2, v10, v3
	v_and_b32_e32 v3, 0xffff0000, v4
	v_fmac_f32_e32 v2, v11, v3
	v_lshlrev_b32_e32 v3, 16, v5
	v_fmac_f32_e32 v2, v12, v3
	v_and_b32_e32 v3, 0xffff0000, v5
	v_fmac_f32_e32 v2, v13, v3
	v_add_f32_e32 v14, v14, v2
	v_bitop3_b32 v2, v162, v193, 2 bitop3:0x36
	v_lshl_add_u32 v2, v2, 4, v0
	v_or_b32_e32 v6, 2, v162
	ds_read_b128 v[2:5], v2
	v_lshl_add_u32 v10, v6, 5, s57
	ds_read_b128 v[6:9], v10
	ds_read_b128 v[10:13], v10 offset:16
	s_waitcnt lgkmcnt(2)
	v_lshlrev_b32_e32 v15, 16, v2
	v_and_b32_e32 v2, 0xffff0000, v2
	s_waitcnt lgkmcnt(1)
	v_mul_f32_e32 v2, v7, v2
	v_fmac_f32_e32 v2, v6, v15
	v_lshlrev_b32_e32 v6, 16, v3
	v_fmac_f32_e32 v2, v8, v6
	v_and_b32_e32 v3, 0xffff0000, v3
	v_fmac_f32_e32 v2, v9, v3
	v_lshlrev_b32_e32 v3, 16, v4
	s_waitcnt lgkmcnt(0)
	v_fmac_f32_e32 v2, v10, v3
	v_and_b32_e32 v3, 0xffff0000, v4
	v_fmac_f32_e32 v2, v11, v3
	v_lshlrev_b32_e32 v3, 16, v5
	v_fmac_f32_e32 v2, v12, v3
	v_and_b32_e32 v3, 0xffff0000, v5
	v_fmac_f32_e32 v2, v13, v3
	v_add_f32_e32 v14, v14, v2
	v_bitop3_b32 v2, v162, v193, 3 bitop3:0x36
	v_lshl_add_u32 v0, v2, 4, v0
	v_or_b32_e32 v6, 3, v162
	ds_read_b128 v[2:5], v0
	v_lshl_add_u32 v0, v6, 5, s57
	ds_read_b128 v[6:9], v0
	ds_read_b128 v[10:13], v0 offset:16
	s_waitcnt lgkmcnt(2)
	v_and_b32_e32 v0, 0xffff0000, v2
	v_lshlrev_b32_e32 v15, 16, v2
	s_waitcnt lgkmcnt(1)
	v_mul_f32_e32 v0, v7, v0
	v_fmac_f32_e32 v0, v6, v15
	v_lshlrev_b32_e32 v2, 16, v3
	v_fmac_f32_e32 v0, v8, v2
	v_and_b32_e32 v2, 0xffff0000, v3
	v_fmac_f32_e32 v0, v9, v2
	v_lshlrev_b32_e32 v2, 16, v4
	s_waitcnt lgkmcnt(0)
	v_fmac_f32_e32 v0, v10, v2
	v_and_b32_e32 v2, 0xffff0000, v4
	v_fmac_f32_e32 v0, v11, v2
	v_lshlrev_b32_e32 v2, 16, v5
	v_fmac_f32_e32 v0, v12, v2
	v_and_b32_e32 v2, 0xffff0000, v5
	v_fmac_f32_e32 v0, v13, v2
	v_add_f32_e32 v0, v14, v0
	v_xor_b32_e32 v2, 4, v56
	ds_bpermute_b32 v2, v2, v0
	s_waitcnt lgkmcnt(0)
	v_add_f32_e32 v0, v0, v2
	v_xor_b32_e32 v2, 8, v56
	ds_bpermute_b32 v2, v2, v0
	s_and_saveexec_b64 s[2:3], vcc
	s_cbranch_execz .LBB0_631
	s_waitcnt lgkmcnt(0)
	v_add_f32_e32 v0, v0, v2
	v_lshl_add_u32 v2, v107, 2, 0
	v_add_u32_e32 v2, 0x20600, v2
	ds_write_b32 v2, v0
